# EpiUp fast path with dwordx4 row-contiguous stores (ds_swizzle exchange between lane halves) + flat->global
# speedup vs baseline: 1.0035x; 1.0035x over previous
.Lupf_u0_entry:
	v_mbcnt_lo_u32_b32 v253, -1, 0
	v_mbcnt_hi_u32_b32 v253, -1, v253
	v_and_b32_e32 v254, 15, v253
	v_lshrrev_b32_e32 v255, 4, v253
	s_lshr_b32 s100, s3, 6
	s_lshr_b32 s101, s100, 2
	s_and_b32 s100, s100, 3
	s_lshl_b32 vcc_lo, s101, 6
	v_add_u32_e32 v251, vcc_lo, v254
	s_add_i32 vcc_hi, s98, -1
	v_add_u32_e32 v250, vcc_hi, v251
	v_mul_u32_u24_e32 v250, 0x1600, v250
	s_lshl_b32 vcc_lo, s28, 7
	s_lshl_b32 vcc_hi, s100, 5
	s_add_i32 vcc_lo, vcc_lo, vcc_hi
	v_lshl_add_u32 v253, v255, 2, vcc_lo
	v_and_b32_e32 v252, 1, v255
	v_lshlrev_b32_e32 v252, 1, v252
	v_lshrrev_b32_e32 v245, 1, v255
	v_or_b32_e32 v252, v252, v245
	v_lshl_add_u32 v252, v252, 3, vcc_lo
	v_lshl_add_u32 v250, v252, 1, v250
	v_lshlrev_b32_e32 v146, 2, v253
	v_add_u32_e32 v147, 0x5800, v146
	v_add_u32_e32 v168, 0xb000, v146
	v_add_u32_e32 v169, 0x2c00, v146
	v_add_u32_e32 v245, 0x8400, v146
	v_add_u32_e32 v252, 0xdc00, v146
	global_load_dwordx4 v[172:175], v146, s[62:63] offset:0
	global_load_dwordx4 v[176:179], v147, s[62:63] offset:0
	global_load_dwordx4 v[180:183], v168, s[62:63] offset:0
	global_load_dwordx4 v[188:191], v169, s[62:63] offset:0
	global_load_dwordx4 v[192:195], v245, s[62:63] offset:0
	global_load_dwordx4 v[196:199], v252, s[62:63] offset:0
	global_load_dwordx4 v[184:187], v146, s[64:65] offset:0
	global_load_dwordx4 v[200:203], v169, s[64:65] offset:0
	s_lshl_b32 s101, s101, 11
	s_lshl_b32 s100, s100, 7
	s_add_i32 s101, s101, s100
	s_add_i32 s101, s101, 0x20000
	v_lshl_add_u32 v249, v255, 4, s101
	v_add_u32_e32 v253, 0x400, v249
	v_cmp_eq_u32_e64 s[98:99], 0, v254
	v_cmp_eq_u32_e32 vcc, 15, v254
	s_nop 4
	s_mov_b64 exec, s[98:99]
	ds_write_b128 v253, v[124:127] offset:0
	ds_write_b128 v253, v[108:111] offset:64
	ds_write_b128 v253, v[112:115] offset:512
	ds_write_b128 v253, v[84:87] offset:576
	ds_write_b128 v253, v[72:75] offset:4096
	ds_write_b128 v253, v[44:47] offset:4160
	ds_write_b128 v253, v[48:51] offset:4608
	ds_write_b128 v253, v[20:23] offset:4672
	s_mov_b64 exec, vcc
	ds_write_b128 v253, v[104:107] offset:1024
	ds_write_b128 v253, v[76:79] offset:1088
	ds_write_b128 v253, v[80:83] offset:1536
	ds_write_b128 v253, v[52:55] offset:1600
	ds_write_b128 v253, v[40:43] offset:5120
	ds_write_b128 v253, v[12:15] offset:5184
	ds_write_b128 v253, v[16:19] offset:5632
	ds_write_b128 v253, v[0:3] offset:5696
	s_mov_b64 exec, -1
	s_waitcnt lgkmcnt(0)
	s_barrier
	ds_read_b128 v[204:207], v249 offset:0
	ds_read_b128 v[208:211], v249 offset:512
	ds_read_b128 v[160:163], v249 offset:3072
	ds_read_b128 v[164:167], v249 offset:3584
	s_waitcnt vmcnt(0) lgkmcnt(0)
	v_cndmask_b32_e32 v148, v124, v204, vcc
	v_cndmask_b32_e32 v149, v125, v205, vcc
	v_cndmask_b32_e32 v150, v126, v206, vcc
	v_cndmask_b32_e32 v151, v127, v207, vcc
	v_cndmask_b32_e64 v152, v124, v120, s[98:99]
	v_cndmask_b32_e64 v153, v125, v121, s[98:99]
	v_cndmask_b32_e64 v154, v126, v122, s[98:99]
	v_cndmask_b32_e64 v155, v127, v123, s[98:99]
	v_fma_f32 v156, v176, v124, v184
	v_fma_f32 v157, v177, v125, v185
	v_fma_f32 v158, v178, v126, v186
	v_fma_f32 v159, v179, v127, v187
	v_fmac_f32_dpp v156, v148, v172 row_ror:1 row_mask:0xf bank_mask:0xf
	v_fmac_f32_dpp v157, v149, v173 row_ror:1 row_mask:0xf bank_mask:0xf
	v_fmac_f32_dpp v158, v150, v174 row_ror:1 row_mask:0xf bank_mask:0xf
	v_fmac_f32_dpp v159, v151, v175 row_ror:1 row_mask:0xf bank_mask:0xf
	v_fmac_f32_dpp v156, v152, v180 row_ror:15 row_mask:0xf bank_mask:0xf
	v_fmac_f32_dpp v157, v153, v181 row_ror:15 row_mask:0xf bank_mask:0xf
	v_fmac_f32_dpp v158, v154, v182 row_ror:15 row_mask:0xf bank_mask:0xf
	v_fmac_f32_dpp v159, v155, v183 row_ror:15 row_mask:0xf bank_mask:0xf
	v_cndmask_b32_e32 v148, v112, v208, vcc
	v_cndmask_b32_e32 v149, v113, v209, vcc
	v_cndmask_b32_e32 v150, v114, v210, vcc
	v_cndmask_b32_e32 v151, v115, v211, vcc
	v_cndmask_b32_e64 v152, v112, v100, s[98:99]
	v_cndmask_b32_e64 v153, v113, v101, s[98:99]
	v_cndmask_b32_e64 v154, v114, v102, s[98:99]
	v_cndmask_b32_e64 v155, v115, v103, s[98:99]
	v_fma_f32 v237, v192, v112, v200
	v_fma_f32 v238, v193, v113, v201
	v_fma_f32 v239, v194, v114, v202
	v_fma_f32 v240, v195, v115, v203
	v_fmac_f32_dpp v237, v148, v188 row_ror:1 row_mask:0xf bank_mask:0xf
	v_fmac_f32_dpp v238, v149, v189 row_ror:1 row_mask:0xf bank_mask:0xf
	v_fmac_f32_dpp v239, v150, v190 row_ror:1 row_mask:0xf bank_mask:0xf
	v_fmac_f32_dpp v240, v151, v191 row_ror:1 row_mask:0xf bank_mask:0xf
	v_fmac_f32_dpp v237, v152, v196 row_ror:15 row_mask:0xf bank_mask:0xf
	v_fmac_f32_dpp v238, v153, v197 row_ror:15 row_mask:0xf bank_mask:0xf
	v_fmac_f32_dpp v239, v154, v198 row_ror:15 row_mask:0xf bank_mask:0xf
	v_fmac_f32_dpp v240, v155, v199 row_ror:15 row_mask:0xf bank_mask:0xf
	v_mul_f32_e32 v148, 0xbfb8aa3b, v156
	v_mul_f32_e32 v149, 0xbfb8aa3b, v157
	v_mul_f32_e32 v150, 0xbfb8aa3b, v158
	v_mul_f32_e32 v151, 0xbfb8aa3b, v159
	v_exp_f32_e32 v148, v148
	v_exp_f32_e32 v149, v149
	v_exp_f32_e32 v150, v150
	v_exp_f32_e32 v151, v151
	v_add_f32_e32 v148, 1.0, v148
	v_add_f32_e32 v149, 1.0, v149
	v_add_f32_e32 v150, 1.0, v150
	v_add_f32_e32 v151, 1.0, v151
	v_rcp_f32_e32 v148, v148
	v_rcp_f32_e32 v149, v149
	v_rcp_f32_e32 v150, v150
	v_rcp_f32_e32 v151, v151
	v_mul_f32_e32 v156, v156, v148
	v_mul_f32_e32 v157, v157, v149
	v_mul_f32_e32 v158, v158, v150
	v_mul_f32_e32 v159, v159, v151
	v_mul_f32_e32 v156, v156, v237
	v_mul_f32_e32 v157, v157, v238
	v_mul_f32_e32 v158, v158, v239
	v_mul_f32_e32 v159, v159, v240
	v_cvt_pk_bf16_f32 v241, v156, v157
	v_cvt_pk_bf16_f32 v242, v158, v159
	ds_read_b128 v[204:207], v249 offset:4096
	ds_read_b128 v[208:211], v249 offset:4608
	v_cndmask_b32_e32 v148, v120, v124, vcc
	v_cndmask_b32_e32 v149, v121, v125, vcc
	v_cndmask_b32_e32 v150, v122, v126, vcc
	v_cndmask_b32_e32 v151, v123, v127, vcc
	v_cndmask_b32_e64 v152, v120, v116, s[98:99]
	v_cndmask_b32_e64 v153, v121, v117, s[98:99]
	v_cndmask_b32_e64 v154, v122, v118, s[98:99]
	v_cndmask_b32_e64 v155, v123, v119, s[98:99]
	v_fma_f32 v156, v176, v120, v184
	v_fma_f32 v157, v177, v121, v185
	v_fma_f32 v158, v178, v122, v186
	v_fma_f32 v159, v179, v123, v187
	v_fmac_f32_dpp v156, v148, v172 row_ror:1 row_mask:0xf bank_mask:0xf
	v_fmac_f32_dpp v157, v149, v173 row_ror:1 row_mask:0xf bank_mask:0xf
	v_fmac_f32_dpp v158, v150, v174 row_ror:1 row_mask:0xf bank_mask:0xf
	v_fmac_f32_dpp v159, v151, v175 row_ror:1 row_mask:0xf bank_mask:0xf
	v_fmac_f32_dpp v156, v152, v180 row_ror:15 row_mask:0xf bank_mask:0xf
	v_fmac_f32_dpp v157, v153, v181 row_ror:15 row_mask:0xf bank_mask:0xf
	v_fmac_f32_dpp v158, v154, v182 row_ror:15 row_mask:0xf bank_mask:0xf
	v_fmac_f32_dpp v159, v155, v183 row_ror:15 row_mask:0xf bank_mask:0xf
	v_cndmask_b32_e32 v148, v100, v112, vcc
	v_cndmask_b32_e32 v149, v101, v113, vcc
	v_cndmask_b32_e32 v150, v102, v114, vcc
	v_cndmask_b32_e32 v151, v103, v115, vcc
	v_cndmask_b32_e64 v152, v100, v92, s[98:99]
	v_cndmask_b32_e64 v153, v101, v93, s[98:99]
	v_cndmask_b32_e64 v154, v102, v94, s[98:99]
	v_cndmask_b32_e64 v155, v103, v95, s[98:99]
	v_fma_f32 v237, v192, v100, v200
	v_fma_f32 v238, v193, v101, v201
	v_fma_f32 v239, v194, v102, v202
	v_fma_f32 v240, v195, v103, v203
	v_fmac_f32_dpp v237, v148, v188 row_ror:1 row_mask:0xf bank_mask:0xf
	v_fmac_f32_dpp v238, v149, v189 row_ror:1 row_mask:0xf bank_mask:0xf
	v_fmac_f32_dpp v239, v150, v190 row_ror:1 row_mask:0xf bank_mask:0xf
	v_fmac_f32_dpp v240, v151, v191 row_ror:1 row_mask:0xf bank_mask:0xf
	v_fmac_f32_dpp v237, v152, v196 row_ror:15 row_mask:0xf bank_mask:0xf
	v_fmac_f32_dpp v238, v153, v197 row_ror:15 row_mask:0xf bank_mask:0xf
	v_fmac_f32_dpp v239, v154, v198 row_ror:15 row_mask:0xf bank_mask:0xf
	v_fmac_f32_dpp v240, v155, v199 row_ror:15 row_mask:0xf bank_mask:0xf
	v_mul_f32_e32 v148, 0xbfb8aa3b, v156
	v_mul_f32_e32 v149, 0xbfb8aa3b, v157
	v_mul_f32_e32 v150, 0xbfb8aa3b, v158
	v_mul_f32_e32 v151, 0xbfb8aa3b, v159
	v_exp_f32_e32 v148, v148
	v_exp_f32_e32 v149, v149
	v_exp_f32_e32 v150, v150
	v_exp_f32_e32 v151, v151
	v_add_f32_e32 v148, 1.0, v148
	v_add_f32_e32 v149, 1.0, v149
	v_add_f32_e32 v150, 1.0, v150
	v_add_f32_e32 v151, 1.0, v151
	v_rcp_f32_e32 v148, v148
	v_rcp_f32_e32 v149, v149
	v_rcp_f32_e32 v150, v150
	v_rcp_f32_e32 v151, v151
	v_mul_f32_e32 v156, v156, v148
	v_mul_f32_e32 v157, v157, v149
	v_mul_f32_e32 v158, v158, v150
	v_mul_f32_e32 v159, v159, v151
	v_mul_f32_e32 v156, v156, v237
	v_mul_f32_e32 v157, v157, v238
	v_mul_f32_e32 v158, v158, v239
	v_mul_f32_e32 v159, v159, v240
	v_cvt_pk_bf16_f32 v243, v156, v157
	v_cvt_pk_bf16_f32 v244, v158, v159
	v_cndmask_b32_e32 v148, v116, v120, vcc
	v_cndmask_b32_e32 v149, v117, v121, vcc
	v_cndmask_b32_e32 v150, v118, v122, vcc
	v_cndmask_b32_e32 v151, v119, v123, vcc
	v_cndmask_b32_e64 v152, v116, v104, s[98:99]
	v_cndmask_b32_e64 v153, v117, v105, s[98:99]
	v_cndmask_b32_e64 v154, v118, v106, s[98:99]
	v_cndmask_b32_e64 v155, v119, v107, s[98:99]
	v_fma_f32 v156, v176, v116, v184
	v_fma_f32 v157, v177, v117, v185
	v_fma_f32 v158, v178, v118, v186
	v_fma_f32 v159, v179, v119, v187
	v_fmac_f32_dpp v156, v148, v172 row_ror:1 row_mask:0xf bank_mask:0xf
	v_fmac_f32_dpp v157, v149, v173 row_ror:1 row_mask:0xf bank_mask:0xf
	v_fmac_f32_dpp v158, v150, v174 row_ror:1 row_mask:0xf bank_mask:0xf
	v_fmac_f32_dpp v159, v151, v175 row_ror:1 row_mask:0xf bank_mask:0xf
	v_fmac_f32_dpp v156, v152, v180 row_ror:15 row_mask:0xf bank_mask:0xf
	v_fmac_f32_dpp v157, v153, v181 row_ror:15 row_mask:0xf bank_mask:0xf
	v_fmac_f32_dpp v158, v154, v182 row_ror:15 row_mask:0xf bank_mask:0xf
	v_fmac_f32_dpp v159, v155, v183 row_ror:15 row_mask:0xf bank_mask:0xf
	v_cndmask_b32_e32 v148, v92, v100, vcc
	v_cndmask_b32_e32 v149, v93, v101, vcc
	v_cndmask_b32_e32 v150, v94, v102, vcc
	v_cndmask_b32_e32 v151, v95, v103, vcc
	v_cndmask_b32_e64 v152, v92, v80, s[98:99]
	v_cndmask_b32_e64 v153, v93, v81, s[98:99]
	v_cndmask_b32_e64 v154, v94, v82, s[98:99]
	v_cndmask_b32_e64 v155, v95, v83, s[98:99]
	v_fma_f32 v237, v192, v92, v200
	v_fma_f32 v238, v193, v93, v201
	v_fma_f32 v239, v194, v94, v202
	v_fma_f32 v240, v195, v95, v203
	v_fmac_f32_dpp v237, v148, v188 row_ror:1 row_mask:0xf bank_mask:0xf
	v_fmac_f32_dpp v238, v149, v189 row_ror:1 row_mask:0xf bank_mask:0xf
	v_fmac_f32_dpp v239, v150, v190 row_ror:1 row_mask:0xf bank_mask:0xf
	v_fmac_f32_dpp v240, v151, v191 row_ror:1 row_mask:0xf bank_mask:0xf
	v_fmac_f32_dpp v237, v152, v196 row_ror:15 row_mask:0xf bank_mask:0xf
	v_fmac_f32_dpp v238, v153, v197 row_ror:15 row_mask:0xf bank_mask:0xf
	v_fmac_f32_dpp v239, v154, v198 row_ror:15 row_mask:0xf bank_mask:0xf
	v_fmac_f32_dpp v240, v155, v199 row_ror:15 row_mask:0xf bank_mask:0xf
	v_mul_f32_e32 v148, 0xbfb8aa3b, v156
	v_mul_f32_e32 v149, 0xbfb8aa3b, v157
	v_mul_f32_e32 v150, 0xbfb8aa3b, v158
	v_mul_f32_e32 v151, 0xbfb8aa3b, v159
	v_exp_f32_e32 v148, v148
	v_exp_f32_e32 v149, v149
	v_exp_f32_e32 v150, v150
	v_exp_f32_e32 v151, v151
	v_add_f32_e32 v148, 1.0, v148
	v_add_f32_e32 v149, 1.0, v149
	v_add_f32_e32 v150, 1.0, v150
	v_add_f32_e32 v151, 1.0, v151
	v_rcp_f32_e32 v148, v148
	v_rcp_f32_e32 v149, v149
	v_rcp_f32_e32 v150, v150
	v_rcp_f32_e32 v151, v151
	v_mul_f32_e32 v156, v156, v148
	v_mul_f32_e32 v157, v157, v149
	v_mul_f32_e32 v158, v158, v150
	v_mul_f32_e32 v159, v159, v151
	v_mul_f32_e32 v156, v156, v237
	v_mul_f32_e32 v157, v157, v238
	v_mul_f32_e32 v158, v158, v239
	v_mul_f32_e32 v159, v159, v240
	v_cvt_pk_bf16_f32 v253, v156, v157
	v_cvt_pk_bf16_f32 v254, v158, v159
	v_cndmask_b32_e32 v148, v104, v116, vcc
	v_cndmask_b32_e32 v149, v105, v117, vcc
	v_cndmask_b32_e32 v150, v106, v118, vcc
	v_cndmask_b32_e32 v151, v107, v119, vcc
	v_cndmask_b32_e64 v152, v104, v160, s[98:99]
	v_cndmask_b32_e64 v153, v105, v161, s[98:99]
	v_cndmask_b32_e64 v154, v106, v162, s[98:99]
	v_cndmask_b32_e64 v155, v107, v163, s[98:99]
	v_fma_f32 v156, v176, v104, v184
	v_fma_f32 v157, v177, v105, v185
	v_fma_f32 v158, v178, v106, v186
	v_fma_f32 v159, v179, v107, v187
	v_fmac_f32_dpp v156, v148, v172 row_ror:1 row_mask:0xf bank_mask:0xf
	v_fmac_f32_dpp v157, v149, v173 row_ror:1 row_mask:0xf bank_mask:0xf
	v_fmac_f32_dpp v158, v150, v174 row_ror:1 row_mask:0xf bank_mask:0xf
	v_fmac_f32_dpp v159, v151, v175 row_ror:1 row_mask:0xf bank_mask:0xf
	v_fmac_f32_dpp v156, v152, v180 row_ror:15 row_mask:0xf bank_mask:0xf
	v_fmac_f32_dpp v157, v153, v181 row_ror:15 row_mask:0xf bank_mask:0xf
	v_fmac_f32_dpp v158, v154, v182 row_ror:15 row_mask:0xf bank_mask:0xf
	v_fmac_f32_dpp v159, v155, v183 row_ror:15 row_mask:0xf bank_mask:0xf
	v_cndmask_b32_e32 v148, v80, v92, vcc
	v_cndmask_b32_e32 v149, v81, v93, vcc
	v_cndmask_b32_e32 v150, v82, v94, vcc
	v_cndmask_b32_e32 v151, v83, v95, vcc
	v_cndmask_b32_e64 v152, v80, v164, s[98:99]
	v_cndmask_b32_e64 v153, v81, v165, s[98:99]
	v_cndmask_b32_e64 v154, v82, v166, s[98:99]
	v_cndmask_b32_e64 v155, v83, v167, s[98:99]
	v_fma_f32 v237, v192, v80, v200
	v_fma_f32 v238, v193, v81, v201
	v_fma_f32 v239, v194, v82, v202
	v_fma_f32 v240, v195, v83, v203
	v_fmac_f32_dpp v237, v148, v188 row_ror:1 row_mask:0xf bank_mask:0xf
	v_fmac_f32_dpp v238, v149, v189 row_ror:1 row_mask:0xf bank_mask:0xf
	v_fmac_f32_dpp v239, v150, v190 row_ror:1 row_mask:0xf bank_mask:0xf
	v_fmac_f32_dpp v240, v151, v191 row_ror:1 row_mask:0xf bank_mask:0xf
	v_fmac_f32_dpp v237, v152, v196 row_ror:15 row_mask:0xf bank_mask:0xf
	v_fmac_f32_dpp v238, v153, v197 row_ror:15 row_mask:0xf bank_mask:0xf
	v_fmac_f32_dpp v239, v154, v198 row_ror:15 row_mask:0xf bank_mask:0xf
	v_fmac_f32_dpp v240, v155, v199 row_ror:15 row_mask:0xf bank_mask:0xf
	v_mul_f32_e32 v148, 0xbfb8aa3b, v156
	v_mul_f32_e32 v149, 0xbfb8aa3b, v157
	v_mul_f32_e32 v150, 0xbfb8aa3b, v158
	v_mul_f32_e32 v151, 0xbfb8aa3b, v159
	v_exp_f32_e32 v148, v148
	v_exp_f32_e32 v149, v149
	v_exp_f32_e32 v150, v150
	v_exp_f32_e32 v151, v151
	v_add_f32_e32 v148, 1.0, v148
	v_add_f32_e32 v149, 1.0, v149
	v_add_f32_e32 v150, 1.0, v150
	v_add_f32_e32 v151, 1.0, v151
	v_rcp_f32_e32 v148, v148
	v_rcp_f32_e32 v149, v149
	v_rcp_f32_e32 v150, v150
	v_rcp_f32_e32 v151, v151
	v_mul_f32_e32 v156, v156, v148
	v_mul_f32_e32 v157, v157, v149
	v_mul_f32_e32 v158, v158, v150
	v_mul_f32_e32 v159, v159, v151
	v_mul_f32_e32 v156, v156, v237
	v_mul_f32_e32 v157, v157, v238
	v_mul_f32_e32 v158, v158, v239
	v_mul_f32_e32 v159, v159, v240
	v_cvt_pk_bf16_f32 v255, v156, v157
	v_cvt_pk_bf16_f32 v246, v158, v159
	global_load_dwordx4 v[124:127], v146, s[62:63] offset:64
	global_load_dwordx4 v[120:123], v147, s[62:63] offset:64
	global_load_dwordx4 v[116:119], v168, s[62:63] offset:64
	global_load_dwordx4 v[112:115], v169, s[62:63] offset:64
	global_load_dwordx4 v[100:103], v245, s[62:63] offset:64
	global_load_dwordx4 v[92:95], v252, s[62:63] offset:64
	global_load_dwordx4 v[104:107], v146, s[64:65] offset:64
	global_load_dwordx4 v[80:83], v169, s[64:65] offset:64
	ds_read_b128 v[160:163], v249 offset:7168
	ds_read_b128 v[164:167], v249 offset:7680
	s_waitcnt lgkmcnt(2)
	v_cndmask_b32_e32 v148, v72, v204, vcc
	v_cndmask_b32_e32 v149, v73, v205, vcc
	v_cndmask_b32_e32 v150, v74, v206, vcc
	v_cndmask_b32_e32 v151, v75, v207, vcc
	v_cndmask_b32_e64 v152, v72, v64, s[98:99]
	v_cndmask_b32_e64 v153, v73, v65, s[98:99]
	v_cndmask_b32_e64 v154, v74, v66, s[98:99]
	v_cndmask_b32_e64 v155, v75, v67, s[98:99]
	v_fma_f32 v156, v176, v72, v184
	v_fma_f32 v157, v177, v73, v185
	v_fma_f32 v158, v178, v74, v186
	v_fma_f32 v159, v179, v75, v187
	v_fmac_f32_dpp v156, v148, v172 row_ror:1 row_mask:0xf bank_mask:0xf
	v_fmac_f32_dpp v157, v149, v173 row_ror:1 row_mask:0xf bank_mask:0xf
	v_fmac_f32_dpp v158, v150, v174 row_ror:1 row_mask:0xf bank_mask:0xf
	v_fmac_f32_dpp v159, v151, v175 row_ror:1 row_mask:0xf bank_mask:0xf
	v_fmac_f32_dpp v156, v152, v180 row_ror:15 row_mask:0xf bank_mask:0xf
	v_fmac_f32_dpp v157, v153, v181 row_ror:15 row_mask:0xf bank_mask:0xf
	v_fmac_f32_dpp v158, v154, v182 row_ror:15 row_mask:0xf bank_mask:0xf
	v_fmac_f32_dpp v159, v155, v183 row_ror:15 row_mask:0xf bank_mask:0xf
	v_cndmask_b32_e32 v148, v48, v208, vcc
	v_cndmask_b32_e32 v149, v49, v209, vcc
	v_cndmask_b32_e32 v150, v50, v210, vcc
	v_cndmask_b32_e32 v151, v51, v211, vcc
	v_cndmask_b32_e64 v152, v48, v36, s[98:99]
	v_cndmask_b32_e64 v153, v49, v37, s[98:99]
	v_cndmask_b32_e64 v154, v50, v38, s[98:99]
	v_cndmask_b32_e64 v155, v51, v39, s[98:99]
	v_fma_f32 v237, v192, v48, v200
	v_fma_f32 v238, v193, v49, v201
	v_fma_f32 v239, v194, v50, v202
	v_fma_f32 v240, v195, v51, v203
	v_fmac_f32_dpp v237, v148, v188 row_ror:1 row_mask:0xf bank_mask:0xf
	v_fmac_f32_dpp v238, v149, v189 row_ror:1 row_mask:0xf bank_mask:0xf
	v_fmac_f32_dpp v239, v150, v190 row_ror:1 row_mask:0xf bank_mask:0xf
	v_fmac_f32_dpp v240, v151, v191 row_ror:1 row_mask:0xf bank_mask:0xf
	v_fmac_f32_dpp v237, v152, v196 row_ror:15 row_mask:0xf bank_mask:0xf
	v_fmac_f32_dpp v238, v153, v197 row_ror:15 row_mask:0xf bank_mask:0xf
	v_fmac_f32_dpp v239, v154, v198 row_ror:15 row_mask:0xf bank_mask:0xf
	v_fmac_f32_dpp v240, v155, v199 row_ror:15 row_mask:0xf bank_mask:0xf
	v_mul_f32_e32 v148, 0xbfb8aa3b, v156
	v_mul_f32_e32 v149, 0xbfb8aa3b, v157
	v_mul_f32_e32 v150, 0xbfb8aa3b, v158
	v_mul_f32_e32 v151, 0xbfb8aa3b, v159
	v_exp_f32_e32 v148, v148
	v_exp_f32_e32 v149, v149
	v_exp_f32_e32 v150, v150
	v_exp_f32_e32 v151, v151
	v_add_f32_e32 v148, 1.0, v148
	v_add_f32_e32 v149, 1.0, v149
	v_add_f32_e32 v150, 1.0, v150
	v_add_f32_e32 v151, 1.0, v151
	v_rcp_f32_e32 v148, v148
	v_rcp_f32_e32 v149, v149
	v_rcp_f32_e32 v150, v150
	v_rcp_f32_e32 v151, v151
	v_mul_f32_e32 v156, v156, v148
	v_mul_f32_e32 v157, v157, v149
	v_mul_f32_e32 v158, v158, v150
	v_mul_f32_e32 v159, v159, v151
	v_mul_f32_e32 v156, v156, v237
	v_mul_f32_e32 v157, v157, v238
	v_mul_f32_e32 v158, v158, v239
	v_mul_f32_e32 v159, v159, v240
	v_cvt_pk_bf16_f32 v247, v156, v157
	v_cvt_pk_bf16_f32 v248, v158, v159
	ds_read_b128 v[204:207], v249 offset:64
	ds_read_b128 v[208:211], v249 offset:576
	v_cndmask_b32_e32 v148, v64, v72, vcc
	v_cndmask_b32_e32 v149, v65, v73, vcc
	v_cndmask_b32_e32 v150, v66, v74, vcc
	v_cndmask_b32_e32 v151, v67, v75, vcc
	v_cndmask_b32_e64 v152, v64, v56, s[98:99]
	v_cndmask_b32_e64 v153, v65, v57, s[98:99]
	v_cndmask_b32_e64 v154, v66, v58, s[98:99]
	v_cndmask_b32_e64 v155, v67, v59, s[98:99]
	v_fma_f32 v156, v176, v64, v184
	v_fma_f32 v157, v177, v65, v185
	v_fma_f32 v158, v178, v66, v186
	v_fma_f32 v159, v179, v67, v187
	v_fmac_f32_dpp v156, v148, v172 row_ror:1 row_mask:0xf bank_mask:0xf
	v_fmac_f32_dpp v157, v149, v173 row_ror:1 row_mask:0xf bank_mask:0xf
	v_fmac_f32_dpp v158, v150, v174 row_ror:1 row_mask:0xf bank_mask:0xf
	v_fmac_f32_dpp v159, v151, v175 row_ror:1 row_mask:0xf bank_mask:0xf
	v_fmac_f32_dpp v156, v152, v180 row_ror:15 row_mask:0xf bank_mask:0xf
	v_fmac_f32_dpp v157, v153, v181 row_ror:15 row_mask:0xf bank_mask:0xf
	v_fmac_f32_dpp v158, v154, v182 row_ror:15 row_mask:0xf bank_mask:0xf
	v_fmac_f32_dpp v159, v155, v183 row_ror:15 row_mask:0xf bank_mask:0xf
	v_cndmask_b32_e32 v148, v36, v48, vcc
	v_cndmask_b32_e32 v149, v37, v49, vcc
	v_cndmask_b32_e32 v150, v38, v50, vcc
	v_cndmask_b32_e32 v151, v39, v51, vcc
	v_cndmask_b32_e64 v152, v36, v28, s[98:99]
	v_cndmask_b32_e64 v153, v37, v29, s[98:99]
	v_cndmask_b32_e64 v154, v38, v30, s[98:99]
	v_cndmask_b32_e64 v155, v39, v31, s[98:99]
	v_fma_f32 v237, v192, v36, v200
	v_fma_f32 v238, v193, v37, v201
	v_fma_f32 v239, v194, v38, v202
	v_fma_f32 v240, v195, v39, v203
	v_fmac_f32_dpp v237, v148, v188 row_ror:1 row_mask:0xf bank_mask:0xf
	v_fmac_f32_dpp v238, v149, v189 row_ror:1 row_mask:0xf bank_mask:0xf
	v_fmac_f32_dpp v239, v150, v190 row_ror:1 row_mask:0xf bank_mask:0xf
	v_fmac_f32_dpp v240, v151, v191 row_ror:1 row_mask:0xf bank_mask:0xf
	v_fmac_f32_dpp v237, v152, v196 row_ror:15 row_mask:0xf bank_mask:0xf
	v_fmac_f32_dpp v238, v153, v197 row_ror:15 row_mask:0xf bank_mask:0xf
	v_fmac_f32_dpp v239, v154, v198 row_ror:15 row_mask:0xf bank_mask:0xf
	v_fmac_f32_dpp v240, v155, v199 row_ror:15 row_mask:0xf bank_mask:0xf
	v_mul_f32_e32 v148, 0xbfb8aa3b, v156
	v_mul_f32_e32 v149, 0xbfb8aa3b, v157
	v_mul_f32_e32 v150, 0xbfb8aa3b, v158
	v_mul_f32_e32 v151, 0xbfb8aa3b, v159
	v_exp_f32_e32 v148, v148
	v_exp_f32_e32 v149, v149
	v_exp_f32_e32 v150, v150
	v_exp_f32_e32 v151, v151
	v_add_f32_e32 v148, 1.0, v148
	v_add_f32_e32 v149, 1.0, v149
	v_add_f32_e32 v150, 1.0, v150
	v_add_f32_e32 v151, 1.0, v151
	v_rcp_f32_e32 v148, v148
	v_rcp_f32_e32 v149, v149
	v_rcp_f32_e32 v150, v150
	v_rcp_f32_e32 v151, v151
	v_mul_f32_e32 v156, v156, v148
	v_mul_f32_e32 v157, v157, v149
	v_mul_f32_e32 v158, v158, v150
	v_mul_f32_e32 v159, v159, v151
	v_mul_f32_e32 v156, v156, v237
	v_mul_f32_e32 v157, v157, v238
	v_mul_f32_e32 v158, v158, v239
	v_mul_f32_e32 v159, v159, v240
	v_cvt_pk_bf16_f32 v72, v156, v157
	v_cvt_pk_bf16_f32 v73, v158, v159
	v_cndmask_b32_e32 v148, v56, v64, vcc
	v_cndmask_b32_e32 v149, v57, v65, vcc
	v_cndmask_b32_e32 v150, v58, v66, vcc
	v_cndmask_b32_e32 v151, v59, v67, vcc
	v_cndmask_b32_e64 v152, v56, v40, s[98:99]
	v_cndmask_b32_e64 v153, v57, v41, s[98:99]
	v_cndmask_b32_e64 v154, v58, v42, s[98:99]
	v_cndmask_b32_e64 v155, v59, v43, s[98:99]
	v_fma_f32 v156, v176, v56, v184
	v_fma_f32 v157, v177, v57, v185
	v_fma_f32 v158, v178, v58, v186
	v_fma_f32 v159, v179, v59, v187
	v_fmac_f32_dpp v156, v148, v172 row_ror:1 row_mask:0xf bank_mask:0xf
	v_fmac_f32_dpp v157, v149, v173 row_ror:1 row_mask:0xf bank_mask:0xf
	v_fmac_f32_dpp v158, v150, v174 row_ror:1 row_mask:0xf bank_mask:0xf
	v_fmac_f32_dpp v159, v151, v175 row_ror:1 row_mask:0xf bank_mask:0xf
	v_fmac_f32_dpp v156, v152, v180 row_ror:15 row_mask:0xf bank_mask:0xf
	v_fmac_f32_dpp v157, v153, v181 row_ror:15 row_mask:0xf bank_mask:0xf
	v_fmac_f32_dpp v158, v154, v182 row_ror:15 row_mask:0xf bank_mask:0xf
	v_fmac_f32_dpp v159, v155, v183 row_ror:15 row_mask:0xf bank_mask:0xf
	v_cndmask_b32_e32 v148, v28, v36, vcc
	v_cndmask_b32_e32 v149, v29, v37, vcc
	v_cndmask_b32_e32 v150, v30, v38, vcc
	v_cndmask_b32_e32 v151, v31, v39, vcc
	v_cndmask_b32_e64 v152, v28, v16, s[98:99]
	v_cndmask_b32_e64 v153, v29, v17, s[98:99]
	v_cndmask_b32_e64 v154, v30, v18, s[98:99]
	v_cndmask_b32_e64 v155, v31, v19, s[98:99]
	v_fma_f32 v237, v192, v28, v200
	v_fma_f32 v238, v193, v29, v201
	v_fma_f32 v239, v194, v30, v202
	v_fma_f32 v240, v195, v31, v203
	v_fmac_f32_dpp v237, v148, v188 row_ror:1 row_mask:0xf bank_mask:0xf
	v_fmac_f32_dpp v238, v149, v189 row_ror:1 row_mask:0xf bank_mask:0xf
	v_fmac_f32_dpp v239, v150, v190 row_ror:1 row_mask:0xf bank_mask:0xf
	v_fmac_f32_dpp v240, v151, v191 row_ror:1 row_mask:0xf bank_mask:0xf
	v_fmac_f32_dpp v237, v152, v196 row_ror:15 row_mask:0xf bank_mask:0xf
	v_fmac_f32_dpp v238, v153, v197 row_ror:15 row_mask:0xf bank_mask:0xf
	v_fmac_f32_dpp v239, v154, v198 row_ror:15 row_mask:0xf bank_mask:0xf
	v_fmac_f32_dpp v240, v155, v199 row_ror:15 row_mask:0xf bank_mask:0xf
	v_mul_f32_e32 v148, 0xbfb8aa3b, v156
	v_mul_f32_e32 v149, 0xbfb8aa3b, v157
	v_mul_f32_e32 v150, 0xbfb8aa3b, v158
	v_mul_f32_e32 v151, 0xbfb8aa3b, v159
	v_exp_f32_e32 v148, v148
	v_exp_f32_e32 v149, v149
	v_exp_f32_e32 v150, v150
	v_exp_f32_e32 v151, v151
	v_add_f32_e32 v148, 1.0, v148
	v_add_f32_e32 v149, 1.0, v149
	v_add_f32_e32 v150, 1.0, v150
	v_add_f32_e32 v151, 1.0, v151
	v_rcp_f32_e32 v148, v148
	v_rcp_f32_e32 v149, v149
	v_rcp_f32_e32 v150, v150
	v_rcp_f32_e32 v151, v151
	v_mul_f32_e32 v156, v156, v148
	v_mul_f32_e32 v157, v157, v149
	v_mul_f32_e32 v158, v158, v150
	v_mul_f32_e32 v159, v159, v151
	v_mul_f32_e32 v156, v156, v237
	v_mul_f32_e32 v157, v157, v238
	v_mul_f32_e32 v158, v158, v239
	v_mul_f32_e32 v159, v159, v240
	v_cvt_pk_bf16_f32 v74, v156, v157
	v_cvt_pk_bf16_f32 v75, v158, v159
	s_waitcnt lgkmcnt(2)
	v_cndmask_b32_e32 v148, v40, v56, vcc
	v_cndmask_b32_e32 v149, v41, v57, vcc
	v_cndmask_b32_e32 v150, v42, v58, vcc
	v_cndmask_b32_e32 v151, v43, v59, vcc
	v_cndmask_b32_e64 v152, v40, v160, s[98:99]
	v_cndmask_b32_e64 v153, v41, v161, s[98:99]
	v_cndmask_b32_e64 v154, v42, v162, s[98:99]
	v_cndmask_b32_e64 v155, v43, v163, s[98:99]
	v_fma_f32 v156, v176, v40, v184
	v_fma_f32 v157, v177, v41, v185
	v_fma_f32 v158, v178, v42, v186
	v_fma_f32 v159, v179, v43, v187
	v_fmac_f32_dpp v156, v148, v172 row_ror:1 row_mask:0xf bank_mask:0xf
	v_fmac_f32_dpp v157, v149, v173 row_ror:1 row_mask:0xf bank_mask:0xf
	v_fmac_f32_dpp v158, v150, v174 row_ror:1 row_mask:0xf bank_mask:0xf
	v_fmac_f32_dpp v159, v151, v175 row_ror:1 row_mask:0xf bank_mask:0xf
	v_fmac_f32_dpp v156, v152, v180 row_ror:15 row_mask:0xf bank_mask:0xf
	v_fmac_f32_dpp v157, v153, v181 row_ror:15 row_mask:0xf bank_mask:0xf
	v_fmac_f32_dpp v158, v154, v182 row_ror:15 row_mask:0xf bank_mask:0xf
	v_fmac_f32_dpp v159, v155, v183 row_ror:15 row_mask:0xf bank_mask:0xf
	v_cndmask_b32_e32 v148, v16, v28, vcc
	v_cndmask_b32_e32 v149, v17, v29, vcc
	v_cndmask_b32_e32 v150, v18, v30, vcc
	v_cndmask_b32_e32 v151, v19, v31, vcc
	v_cndmask_b32_e64 v152, v16, v164, s[98:99]
	v_cndmask_b32_e64 v153, v17, v165, s[98:99]
	v_cndmask_b32_e64 v154, v18, v166, s[98:99]
	v_cndmask_b32_e64 v155, v19, v167, s[98:99]
	v_fma_f32 v237, v192, v16, v200
	v_fma_f32 v238, v193, v17, v201
	v_fma_f32 v239, v194, v18, v202
	v_fma_f32 v240, v195, v19, v203
	v_fmac_f32_dpp v237, v148, v188 row_ror:1 row_mask:0xf bank_mask:0xf
	v_fmac_f32_dpp v238, v149, v189 row_ror:1 row_mask:0xf bank_mask:0xf
	v_fmac_f32_dpp v239, v150, v190 row_ror:1 row_mask:0xf bank_mask:0xf
	v_fmac_f32_dpp v240, v151, v191 row_ror:1 row_mask:0xf bank_mask:0xf
	v_fmac_f32_dpp v237, v152, v196 row_ror:15 row_mask:0xf bank_mask:0xf
	v_fmac_f32_dpp v238, v153, v197 row_ror:15 row_mask:0xf bank_mask:0xf
	v_fmac_f32_dpp v239, v154, v198 row_ror:15 row_mask:0xf bank_mask:0xf
	v_fmac_f32_dpp v240, v155, v199 row_ror:15 row_mask:0xf bank_mask:0xf
	v_mul_f32_e32 v148, 0xbfb8aa3b, v156
	v_mul_f32_e32 v149, 0xbfb8aa3b, v157
	v_mul_f32_e32 v150, 0xbfb8aa3b, v158
	v_mul_f32_e32 v151, 0xbfb8aa3b, v159
	v_exp_f32_e32 v148, v148
	v_exp_f32_e32 v149, v149
	v_exp_f32_e32 v150, v150
	v_exp_f32_e32 v151, v151
	v_add_f32_e32 v148, 1.0, v148
	v_add_f32_e32 v149, 1.0, v149
	v_add_f32_e32 v150, 1.0, v150
	v_add_f32_e32 v151, 1.0, v151
	v_rcp_f32_e32 v148, v148
	v_rcp_f32_e32 v149, v149
	v_rcp_f32_e32 v150, v150
	v_rcp_f32_e32 v151, v151
	v_mul_f32_e32 v156, v156, v148
	v_mul_f32_e32 v157, v157, v149
	v_mul_f32_e32 v158, v158, v150
	v_mul_f32_e32 v159, v159, v151
	v_mul_f32_e32 v156, v156, v237
	v_mul_f32_e32 v157, v157, v238
	v_mul_f32_e32 v158, v158, v239
	v_mul_f32_e32 v159, v159, v240
	v_cvt_pk_bf16_f32 v48, v156, v157
	v_cvt_pk_bf16_f32 v49, v158, v159
	ds_read_b128 v[160:163], v249 offset:3136
	ds_read_b128 v[164:167], v249 offset:3648
	s_waitcnt vmcnt(0) lgkmcnt(0)
	v_mbcnt_lo_u32_b32 v146, -1, 0
	v_mbcnt_hi_u32_b32 v146, -1, v146
	v_bfe_i32 v146, v146, 4, 1
	v_cndmask_b32_e32 v148, v108, v204, vcc
	v_cndmask_b32_e32 v149, v109, v205, vcc
	v_cndmask_b32_e32 v150, v110, v206, vcc
	v_cndmask_b32_e32 v151, v111, v207, vcc
	v_cndmask_b32_e64 v152, v108, v96, s[98:99]
	v_cndmask_b32_e64 v153, v109, v97, s[98:99]
	v_cndmask_b32_e64 v154, v110, v98, s[98:99]
	v_cndmask_b32_e64 v155, v111, v99, s[98:99]
	v_fma_f32 v156, v120, v108, v104
	v_fma_f32 v157, v121, v109, v105
	v_fma_f32 v158, v122, v110, v106
	v_fma_f32 v159, v123, v111, v107
	v_fmac_f32_dpp v156, v148, v124 row_ror:1 row_mask:0xf bank_mask:0xf
	v_fmac_f32_dpp v157, v149, v125 row_ror:1 row_mask:0xf bank_mask:0xf
	v_fmac_f32_dpp v158, v150, v126 row_ror:1 row_mask:0xf bank_mask:0xf
	v_fmac_f32_dpp v159, v151, v127 row_ror:1 row_mask:0xf bank_mask:0xf
	v_fmac_f32_dpp v156, v152, v116 row_ror:15 row_mask:0xf bank_mask:0xf
	v_fmac_f32_dpp v157, v153, v117 row_ror:15 row_mask:0xf bank_mask:0xf
	v_fmac_f32_dpp v158, v154, v118 row_ror:15 row_mask:0xf bank_mask:0xf
	v_fmac_f32_dpp v159, v155, v119 row_ror:15 row_mask:0xf bank_mask:0xf
	v_cndmask_b32_e32 v148, v84, v208, vcc
	v_cndmask_b32_e32 v149, v85, v209, vcc
	v_cndmask_b32_e32 v150, v86, v210, vcc
	v_cndmask_b32_e32 v151, v87, v211, vcc
	v_cndmask_b32_e64 v152, v84, v68, s[98:99]
	v_cndmask_b32_e64 v153, v85, v69, s[98:99]
	v_cndmask_b32_e64 v154, v86, v70, s[98:99]
	v_cndmask_b32_e64 v155, v87, v71, s[98:99]
	v_fma_f32 v237, v100, v84, v80
	v_fma_f32 v238, v101, v85, v81
	v_fma_f32 v239, v102, v86, v82
	v_fma_f32 v240, v103, v87, v83
	v_fmac_f32_dpp v237, v148, v112 row_ror:1 row_mask:0xf bank_mask:0xf
	v_fmac_f32_dpp v238, v149, v113 row_ror:1 row_mask:0xf bank_mask:0xf
	v_fmac_f32_dpp v239, v150, v114 row_ror:1 row_mask:0xf bank_mask:0xf
	v_fmac_f32_dpp v240, v151, v115 row_ror:1 row_mask:0xf bank_mask:0xf
	v_fmac_f32_dpp v237, v152, v92 row_ror:15 row_mask:0xf bank_mask:0xf
	v_fmac_f32_dpp v238, v153, v93 row_ror:15 row_mask:0xf bank_mask:0xf
	v_fmac_f32_dpp v239, v154, v94 row_ror:15 row_mask:0xf bank_mask:0xf
	v_fmac_f32_dpp v240, v155, v95 row_ror:15 row_mask:0xf bank_mask:0xf
	v_mul_f32_e32 v148, 0xbfb8aa3b, v156
	v_mul_f32_e32 v149, 0xbfb8aa3b, v157
	v_mul_f32_e32 v150, 0xbfb8aa3b, v158
	v_mul_f32_e32 v151, 0xbfb8aa3b, v159
	v_exp_f32_e32 v148, v148
	v_exp_f32_e32 v149, v149
	v_exp_f32_e32 v150, v150
	v_exp_f32_e32 v151, v151
	v_add_f32_e32 v148, 1.0, v148
	v_add_f32_e32 v149, 1.0, v149
	v_add_f32_e32 v150, 1.0, v150
	v_add_f32_e32 v151, 1.0, v151
	v_rcp_f32_e32 v148, v148
	v_rcp_f32_e32 v149, v149
	v_rcp_f32_e32 v150, v150
	v_rcp_f32_e32 v151, v151
	v_mul_f32_e32 v156, v156, v148
	v_mul_f32_e32 v157, v157, v149
	v_mul_f32_e32 v158, v158, v150
	v_mul_f32_e32 v159, v159, v151
	v_mul_f32_e32 v156, v156, v237
	v_mul_f32_e32 v157, v157, v238
	v_mul_f32_e32 v158, v158, v239
	v_mul_f32_e32 v159, v159, v240
	v_cvt_pk_bf16_f32 v40, v156, v157
	v_cvt_pk_bf16_f32 v41, v158, v159
	v_bfi_b32 v18, v146, v241, v40
	v_bfi_b32 v19, v146, v242, v41
	ds_swizzle_b32 v16, v18 offset:0x401f
	ds_swizzle_b32 v17, v19 offset:0x401f
	v_mov_b32_e32 v42, v250
	v_lshrrev_b32_e32 v152, 6, v251
	s_nop 1
	v_readfirstlane_b32 s100, v152
	s_waitcnt lgkmcnt(0)
	v_bfi_b32 v148, v146, v16, v241
	v_bfi_b32 v149, v146, v17, v242
	v_bfi_b32 v150, v146, v40, v16
	v_bfi_b32 v151, v146, v41, v17
	s_cmp_eq_u32 s100, 0
	s_cselect_b64 s[100:101], s[98:99], 0
	s_andn2_b64 exec, exec, s[100:101]
	global_store_dwordx4 v42, v[148:151], s[14:15]
	s_mov_b64 exec, -1
	s_nop 1
	ds_read_b128 v[204:207], v249 offset:4160
	ds_read_b128 v[208:211], v249 offset:4672
	v_cndmask_b32_e32 v148, v96, v108, vcc
	v_cndmask_b32_e32 v149, v97, v109, vcc
	v_cndmask_b32_e32 v150, v98, v110, vcc
	v_cndmask_b32_e32 v151, v99, v111, vcc
	v_cndmask_b32_e64 v152, v96, v88, s[98:99]
	v_cndmask_b32_e64 v153, v97, v89, s[98:99]
	v_cndmask_b32_e64 v154, v98, v90, s[98:99]
	v_cndmask_b32_e64 v155, v99, v91, s[98:99]
	v_fma_f32 v156, v120, v96, v104
	v_fma_f32 v157, v121, v97, v105
	v_fma_f32 v158, v122, v98, v106
	v_fma_f32 v159, v123, v99, v107
	v_fmac_f32_dpp v156, v148, v124 row_ror:1 row_mask:0xf bank_mask:0xf
	v_fmac_f32_dpp v157, v149, v125 row_ror:1 row_mask:0xf bank_mask:0xf
	v_fmac_f32_dpp v158, v150, v126 row_ror:1 row_mask:0xf bank_mask:0xf
	v_fmac_f32_dpp v159, v151, v127 row_ror:1 row_mask:0xf bank_mask:0xf
	v_fmac_f32_dpp v156, v152, v116 row_ror:15 row_mask:0xf bank_mask:0xf
	v_fmac_f32_dpp v157, v153, v117 row_ror:15 row_mask:0xf bank_mask:0xf
	v_fmac_f32_dpp v158, v154, v118 row_ror:15 row_mask:0xf bank_mask:0xf
	v_fmac_f32_dpp v159, v155, v119 row_ror:15 row_mask:0xf bank_mask:0xf
	v_cndmask_b32_e32 v148, v68, v84, vcc
	v_cndmask_b32_e32 v149, v69, v85, vcc
	v_cndmask_b32_e32 v150, v70, v86, vcc
	v_cndmask_b32_e32 v151, v71, v87, vcc
	v_cndmask_b32_e64 v152, v68, v60, s[98:99]
	v_cndmask_b32_e64 v153, v69, v61, s[98:99]
	v_cndmask_b32_e64 v154, v70, v62, s[98:99]
	v_cndmask_b32_e64 v155, v71, v63, s[98:99]
	v_fma_f32 v237, v100, v68, v80
	v_fma_f32 v238, v101, v69, v81
	v_fma_f32 v239, v102, v70, v82
	v_fma_f32 v240, v103, v71, v83
	v_fmac_f32_dpp v237, v148, v112 row_ror:1 row_mask:0xf bank_mask:0xf
	v_fmac_f32_dpp v238, v149, v113 row_ror:1 row_mask:0xf bank_mask:0xf
	v_fmac_f32_dpp v239, v150, v114 row_ror:1 row_mask:0xf bank_mask:0xf
	v_fmac_f32_dpp v240, v151, v115 row_ror:1 row_mask:0xf bank_mask:0xf
	v_fmac_f32_dpp v237, v152, v92 row_ror:15 row_mask:0xf bank_mask:0xf
	v_fmac_f32_dpp v238, v153, v93 row_ror:15 row_mask:0xf bank_mask:0xf
	v_fmac_f32_dpp v239, v154, v94 row_ror:15 row_mask:0xf bank_mask:0xf
	v_fmac_f32_dpp v240, v155, v95 row_ror:15 row_mask:0xf bank_mask:0xf
	v_mul_f32_e32 v148, 0xbfb8aa3b, v156
	v_mul_f32_e32 v149, 0xbfb8aa3b, v157
	v_mul_f32_e32 v150, 0xbfb8aa3b, v158
	v_mul_f32_e32 v151, 0xbfb8aa3b, v159
	v_exp_f32_e32 v148, v148
	v_exp_f32_e32 v149, v149
	v_exp_f32_e32 v150, v150
	v_exp_f32_e32 v151, v151
	v_add_f32_e32 v148, 1.0, v148
	v_add_f32_e32 v149, 1.0, v149
	v_add_f32_e32 v150, 1.0, v150
	v_add_f32_e32 v151, 1.0, v151
	v_rcp_f32_e32 v148, v148
	v_rcp_f32_e32 v149, v149
	v_rcp_f32_e32 v150, v150
	v_rcp_f32_e32 v151, v151
	v_mul_f32_e32 v156, v156, v148
	v_mul_f32_e32 v157, v157, v149
	v_mul_f32_e32 v158, v158, v150
	v_mul_f32_e32 v159, v159, v151
	v_mul_f32_e32 v156, v156, v237
	v_mul_f32_e32 v157, v157, v238
	v_mul_f32_e32 v158, v158, v239
	v_mul_f32_e32 v159, v159, v240
	v_cvt_pk_bf16_f32 v40, v156, v157
	v_cvt_pk_bf16_f32 v41, v158, v159
	v_bfi_b32 v18, v146, v243, v40
	v_bfi_b32 v19, v146, v244, v41
	ds_swizzle_b32 v16, v18 offset:0x401f
	ds_swizzle_b32 v17, v19 offset:0x401f
	v_add_u32_e32 v42, 0x16000, v250
	s_waitcnt lgkmcnt(0)
	v_bfi_b32 v148, v146, v16, v243
	v_bfi_b32 v149, v146, v17, v244
	v_bfi_b32 v150, v146, v40, v16
	v_bfi_b32 v151, v146, v41, v17
	global_store_dwordx4 v42, v[148:151], s[14:15]
	s_nop 1
	v_cndmask_b32_e32 v148, v88, v96, vcc
	v_cndmask_b32_e32 v149, v89, v97, vcc
	v_cndmask_b32_e32 v150, v90, v98, vcc
	v_cndmask_b32_e32 v151, v91, v99, vcc
	v_cndmask_b32_e64 v152, v88, v76, s[98:99]
	v_cndmask_b32_e64 v153, v89, v77, s[98:99]
	v_cndmask_b32_e64 v154, v90, v78, s[98:99]
	v_cndmask_b32_e64 v155, v91, v79, s[98:99]
	v_fma_f32 v156, v120, v88, v104
	v_fma_f32 v157, v121, v89, v105
	v_fma_f32 v158, v122, v90, v106
	v_fma_f32 v159, v123, v91, v107
	v_fmac_f32_dpp v156, v148, v124 row_ror:1 row_mask:0xf bank_mask:0xf
	v_fmac_f32_dpp v157, v149, v125 row_ror:1 row_mask:0xf bank_mask:0xf
	v_fmac_f32_dpp v158, v150, v126 row_ror:1 row_mask:0xf bank_mask:0xf
	v_fmac_f32_dpp v159, v151, v127 row_ror:1 row_mask:0xf bank_mask:0xf
	v_fmac_f32_dpp v156, v152, v116 row_ror:15 row_mask:0xf bank_mask:0xf
	v_fmac_f32_dpp v157, v153, v117 row_ror:15 row_mask:0xf bank_mask:0xf
	v_fmac_f32_dpp v158, v154, v118 row_ror:15 row_mask:0xf bank_mask:0xf
	v_fmac_f32_dpp v159, v155, v119 row_ror:15 row_mask:0xf bank_mask:0xf
	v_cndmask_b32_e32 v148, v60, v68, vcc
	v_cndmask_b32_e32 v149, v61, v69, vcc
	v_cndmask_b32_e32 v150, v62, v70, vcc
	v_cndmask_b32_e32 v151, v63, v71, vcc
	v_cndmask_b32_e64 v152, v60, v52, s[98:99]
	v_cndmask_b32_e64 v153, v61, v53, s[98:99]
	v_cndmask_b32_e64 v154, v62, v54, s[98:99]
	v_cndmask_b32_e64 v155, v63, v55, s[98:99]
	v_fma_f32 v237, v100, v60, v80
	v_fma_f32 v238, v101, v61, v81
	v_fma_f32 v239, v102, v62, v82
	v_fma_f32 v240, v103, v63, v83
	v_fmac_f32_dpp v237, v148, v112 row_ror:1 row_mask:0xf bank_mask:0xf
	v_fmac_f32_dpp v238, v149, v113 row_ror:1 row_mask:0xf bank_mask:0xf
	v_fmac_f32_dpp v239, v150, v114 row_ror:1 row_mask:0xf bank_mask:0xf
	v_fmac_f32_dpp v240, v151, v115 row_ror:1 row_mask:0xf bank_mask:0xf
	v_fmac_f32_dpp v237, v152, v92 row_ror:15 row_mask:0xf bank_mask:0xf
	v_fmac_f32_dpp v238, v153, v93 row_ror:15 row_mask:0xf bank_mask:0xf
	v_fmac_f32_dpp v239, v154, v94 row_ror:15 row_mask:0xf bank_mask:0xf
	v_fmac_f32_dpp v240, v155, v95 row_ror:15 row_mask:0xf bank_mask:0xf
	v_mul_f32_e32 v148, 0xbfb8aa3b, v156
	v_mul_f32_e32 v149, 0xbfb8aa3b, v157
	v_mul_f32_e32 v150, 0xbfb8aa3b, v158
	v_mul_f32_e32 v151, 0xbfb8aa3b, v159
	v_exp_f32_e32 v148, v148
	v_exp_f32_e32 v149, v149
	v_exp_f32_e32 v150, v150
	v_exp_f32_e32 v151, v151
	v_add_f32_e32 v148, 1.0, v148
	v_add_f32_e32 v149, 1.0, v149
	v_add_f32_e32 v150, 1.0, v150
	v_add_f32_e32 v151, 1.0, v151
	v_rcp_f32_e32 v148, v148
	v_rcp_f32_e32 v149, v149
	v_rcp_f32_e32 v150, v150
	v_rcp_f32_e32 v151, v151
	v_mul_f32_e32 v156, v156, v148
	v_mul_f32_e32 v157, v157, v149
	v_mul_f32_e32 v158, v158, v150
	v_mul_f32_e32 v159, v159, v151
	v_mul_f32_e32 v156, v156, v237
	v_mul_f32_e32 v157, v157, v238
	v_mul_f32_e32 v158, v158, v239
	v_mul_f32_e32 v159, v159, v240
	v_cvt_pk_bf16_f32 v40, v156, v157
	v_cvt_pk_bf16_f32 v41, v158, v159
	v_bfi_b32 v18, v146, v253, v40
	v_bfi_b32 v19, v146, v254, v41
	ds_swizzle_b32 v16, v18 offset:0x401f
	ds_swizzle_b32 v17, v19 offset:0x401f
	v_add_u32_e32 v42, 0x2c000, v250
	s_waitcnt lgkmcnt(0)
	v_bfi_b32 v148, v146, v16, v253
	v_bfi_b32 v149, v146, v17, v254
	v_bfi_b32 v150, v146, v40, v16
	v_bfi_b32 v151, v146, v41, v17
	global_store_dwordx4 v42, v[148:151], s[14:15]
	s_nop 1
	v_cndmask_b32_e32 v148, v76, v88, vcc
	v_cndmask_b32_e32 v149, v77, v89, vcc
	v_cndmask_b32_e32 v150, v78, v90, vcc
	v_cndmask_b32_e32 v151, v79, v91, vcc
	v_cndmask_b32_e64 v152, v76, v160, s[98:99]
	v_cndmask_b32_e64 v153, v77, v161, s[98:99]
	v_cndmask_b32_e64 v154, v78, v162, s[98:99]
	v_cndmask_b32_e64 v155, v79, v163, s[98:99]
	v_fma_f32 v156, v120, v76, v104
	v_fma_f32 v157, v121, v77, v105
	v_fma_f32 v158, v122, v78, v106
	v_fma_f32 v159, v123, v79, v107
	v_fmac_f32_dpp v156, v148, v124 row_ror:1 row_mask:0xf bank_mask:0xf
	v_fmac_f32_dpp v157, v149, v125 row_ror:1 row_mask:0xf bank_mask:0xf
	v_fmac_f32_dpp v158, v150, v126 row_ror:1 row_mask:0xf bank_mask:0xf
	v_fmac_f32_dpp v159, v151, v127 row_ror:1 row_mask:0xf bank_mask:0xf
	v_fmac_f32_dpp v156, v152, v116 row_ror:15 row_mask:0xf bank_mask:0xf
	v_fmac_f32_dpp v157, v153, v117 row_ror:15 row_mask:0xf bank_mask:0xf
	v_fmac_f32_dpp v158, v154, v118 row_ror:15 row_mask:0xf bank_mask:0xf
	v_fmac_f32_dpp v159, v155, v119 row_ror:15 row_mask:0xf bank_mask:0xf
	v_cndmask_b32_e32 v148, v52, v60, vcc
	v_cndmask_b32_e32 v149, v53, v61, vcc
	v_cndmask_b32_e32 v150, v54, v62, vcc
	v_cndmask_b32_e32 v151, v55, v63, vcc
	v_cndmask_b32_e64 v152, v52, v164, s[98:99]
	v_cndmask_b32_e64 v153, v53, v165, s[98:99]
	v_cndmask_b32_e64 v154, v54, v166, s[98:99]
	v_cndmask_b32_e64 v155, v55, v167, s[98:99]
	v_fma_f32 v237, v100, v52, v80
	v_fma_f32 v238, v101, v53, v81
	v_fma_f32 v239, v102, v54, v82
	v_fma_f32 v240, v103, v55, v83
	v_fmac_f32_dpp v237, v148, v112 row_ror:1 row_mask:0xf bank_mask:0xf
	v_fmac_f32_dpp v238, v149, v113 row_ror:1 row_mask:0xf bank_mask:0xf
	v_fmac_f32_dpp v239, v150, v114 row_ror:1 row_mask:0xf bank_mask:0xf
	v_fmac_f32_dpp v240, v151, v115 row_ror:1 row_mask:0xf bank_mask:0xf
	v_fmac_f32_dpp v237, v152, v92 row_ror:15 row_mask:0xf bank_mask:0xf
	v_fmac_f32_dpp v238, v153, v93 row_ror:15 row_mask:0xf bank_mask:0xf
	v_fmac_f32_dpp v239, v154, v94 row_ror:15 row_mask:0xf bank_mask:0xf
	v_fmac_f32_dpp v240, v155, v95 row_ror:15 row_mask:0xf bank_mask:0xf
	v_mul_f32_e32 v148, 0xbfb8aa3b, v156
	v_mul_f32_e32 v149, 0xbfb8aa3b, v157
	v_mul_f32_e32 v150, 0xbfb8aa3b, v158
	v_mul_f32_e32 v151, 0xbfb8aa3b, v159
	v_exp_f32_e32 v148, v148
	v_exp_f32_e32 v149, v149
	v_exp_f32_e32 v150, v150
	v_exp_f32_e32 v151, v151
	v_add_f32_e32 v148, 1.0, v148
	v_add_f32_e32 v149, 1.0, v149
	v_add_f32_e32 v150, 1.0, v150
	v_add_f32_e32 v151, 1.0, v151
	v_rcp_f32_e32 v148, v148
	v_rcp_f32_e32 v149, v149
	v_rcp_f32_e32 v150, v150
	v_rcp_f32_e32 v151, v151
	v_mul_f32_e32 v156, v156, v148
	v_mul_f32_e32 v157, v157, v149
	v_mul_f32_e32 v158, v158, v150
	v_mul_f32_e32 v159, v159, v151
	v_mul_f32_e32 v156, v156, v237
	v_mul_f32_e32 v157, v157, v238
	v_mul_f32_e32 v158, v158, v239
	v_mul_f32_e32 v159, v159, v240
	v_cvt_pk_bf16_f32 v40, v156, v157
	v_cvt_pk_bf16_f32 v41, v158, v159
	v_bfi_b32 v18, v146, v255, v40
	v_bfi_b32 v19, v146, v246, v41
	ds_swizzle_b32 v16, v18 offset:0x401f
	ds_swizzle_b32 v17, v19 offset:0x401f
	v_add_u32_e32 v42, 0x42000, v250
	s_waitcnt lgkmcnt(0)
	v_bfi_b32 v148, v146, v16, v255
	v_bfi_b32 v149, v146, v17, v246
	v_bfi_b32 v150, v146, v40, v16
	v_bfi_b32 v151, v146, v41, v17
	global_store_dwordx4 v42, v[148:151], s[14:15]
	s_nop 1
	ds_read_b128 v[160:163], v249 offset:7232
	ds_read_b128 v[164:167], v249 offset:7744
	s_waitcnt lgkmcnt(2)
	v_cndmask_b32_e32 v148, v44, v204, vcc
	v_cndmask_b32_e32 v149, v45, v205, vcc
	v_cndmask_b32_e32 v150, v46, v206, vcc
	v_cndmask_b32_e32 v151, v47, v207, vcc
	v_cndmask_b32_e64 v152, v44, v32, s[98:99]
	v_cndmask_b32_e64 v153, v45, v33, s[98:99]
	v_cndmask_b32_e64 v154, v46, v34, s[98:99]
	v_cndmask_b32_e64 v155, v47, v35, s[98:99]
	v_fma_f32 v156, v120, v44, v104
	v_fma_f32 v157, v121, v45, v105
	v_fma_f32 v158, v122, v46, v106
	v_fma_f32 v159, v123, v47, v107
	v_fmac_f32_dpp v156, v148, v124 row_ror:1 row_mask:0xf bank_mask:0xf
	v_fmac_f32_dpp v157, v149, v125 row_ror:1 row_mask:0xf bank_mask:0xf
	v_fmac_f32_dpp v158, v150, v126 row_ror:1 row_mask:0xf bank_mask:0xf
	v_fmac_f32_dpp v159, v151, v127 row_ror:1 row_mask:0xf bank_mask:0xf
	v_fmac_f32_dpp v156, v152, v116 row_ror:15 row_mask:0xf bank_mask:0xf
	v_fmac_f32_dpp v157, v153, v117 row_ror:15 row_mask:0xf bank_mask:0xf
	v_fmac_f32_dpp v158, v154, v118 row_ror:15 row_mask:0xf bank_mask:0xf
	v_fmac_f32_dpp v159, v155, v119 row_ror:15 row_mask:0xf bank_mask:0xf
	v_cndmask_b32_e32 v148, v20, v208, vcc
	v_cndmask_b32_e32 v149, v21, v209, vcc
	v_cndmask_b32_e32 v150, v22, v210, vcc
	v_cndmask_b32_e32 v151, v23, v211, vcc
	v_cndmask_b32_e64 v152, v20, v8, s[98:99]
	v_cndmask_b32_e64 v153, v21, v9, s[98:99]
	v_cndmask_b32_e64 v154, v22, v10, s[98:99]
	v_cndmask_b32_e64 v155, v23, v11, s[98:99]
	v_fma_f32 v237, v100, v20, v80
	v_fma_f32 v238, v101, v21, v81
	v_fma_f32 v239, v102, v22, v82
	v_fma_f32 v240, v103, v23, v83
	v_fmac_f32_dpp v237, v148, v112 row_ror:1 row_mask:0xf bank_mask:0xf
	v_fmac_f32_dpp v238, v149, v113 row_ror:1 row_mask:0xf bank_mask:0xf
	v_fmac_f32_dpp v239, v150, v114 row_ror:1 row_mask:0xf bank_mask:0xf
	v_fmac_f32_dpp v240, v151, v115 row_ror:1 row_mask:0xf bank_mask:0xf
	v_fmac_f32_dpp v237, v152, v92 row_ror:15 row_mask:0xf bank_mask:0xf
	v_fmac_f32_dpp v238, v153, v93 row_ror:15 row_mask:0xf bank_mask:0xf
	v_fmac_f32_dpp v239, v154, v94 row_ror:15 row_mask:0xf bank_mask:0xf
	v_fmac_f32_dpp v240, v155, v95 row_ror:15 row_mask:0xf bank_mask:0xf
	v_mul_f32_e32 v148, 0xbfb8aa3b, v156
	v_mul_f32_e32 v149, 0xbfb8aa3b, v157
	v_mul_f32_e32 v150, 0xbfb8aa3b, v158
	v_mul_f32_e32 v151, 0xbfb8aa3b, v159
	v_exp_f32_e32 v148, v148
	v_exp_f32_e32 v149, v149
	v_exp_f32_e32 v150, v150
	v_exp_f32_e32 v151, v151
	v_add_f32_e32 v148, 1.0, v148
	v_add_f32_e32 v149, 1.0, v149
	v_add_f32_e32 v150, 1.0, v150
	v_add_f32_e32 v151, 1.0, v151
	v_rcp_f32_e32 v148, v148
	v_rcp_f32_e32 v149, v149
	v_rcp_f32_e32 v150, v150
	v_rcp_f32_e32 v151, v151
	v_mul_f32_e32 v156, v156, v148
	v_mul_f32_e32 v157, v157, v149
	v_mul_f32_e32 v158, v158, v150
	v_mul_f32_e32 v159, v159, v151
	v_mul_f32_e32 v156, v156, v237
	v_mul_f32_e32 v157, v157, v238
	v_mul_f32_e32 v158, v158, v239
	v_mul_f32_e32 v159, v159, v240
	v_cvt_pk_bf16_f32 v40, v156, v157
	v_cvt_pk_bf16_f32 v41, v158, v159
	v_bfi_b32 v18, v146, v247, v40
	v_bfi_b32 v19, v146, v248, v41
	ds_swizzle_b32 v16, v18 offset:0x401f
	ds_swizzle_b32 v17, v19 offset:0x401f
	v_add_u32_e32 v42, 0xb0000, v250
	s_waitcnt lgkmcnt(0)
	v_bfi_b32 v148, v146, v16, v247
	v_bfi_b32 v149, v146, v17, v248
	v_bfi_b32 v150, v146, v40, v16
	v_bfi_b32 v151, v146, v41, v17
	global_store_dwordx4 v42, v[148:151], s[14:15]
	s_nop 1
	v_cndmask_b32_e32 v148, v32, v44, vcc
	v_cndmask_b32_e32 v149, v33, v45, vcc
	v_cndmask_b32_e32 v150, v34, v46, vcc
	v_cndmask_b32_e32 v151, v35, v47, vcc
	v_cndmask_b32_e64 v152, v32, v24, s[98:99]
	v_cndmask_b32_e64 v153, v33, v25, s[98:99]
	v_cndmask_b32_e64 v154, v34, v26, s[98:99]
	v_cndmask_b32_e64 v155, v35, v27, s[98:99]
	v_fma_f32 v156, v120, v32, v104
	v_fma_f32 v157, v121, v33, v105
	v_fma_f32 v158, v122, v34, v106
	v_fma_f32 v159, v123, v35, v107
	v_fmac_f32_dpp v156, v148, v124 row_ror:1 row_mask:0xf bank_mask:0xf
	v_fmac_f32_dpp v157, v149, v125 row_ror:1 row_mask:0xf bank_mask:0xf
	v_fmac_f32_dpp v158, v150, v126 row_ror:1 row_mask:0xf bank_mask:0xf
	v_fmac_f32_dpp v159, v151, v127 row_ror:1 row_mask:0xf bank_mask:0xf
	v_fmac_f32_dpp v156, v152, v116 row_ror:15 row_mask:0xf bank_mask:0xf
	v_fmac_f32_dpp v157, v153, v117 row_ror:15 row_mask:0xf bank_mask:0xf
	v_fmac_f32_dpp v158, v154, v118 row_ror:15 row_mask:0xf bank_mask:0xf
	v_fmac_f32_dpp v159, v155, v119 row_ror:15 row_mask:0xf bank_mask:0xf
	v_cndmask_b32_e32 v148, v8, v20, vcc
	v_cndmask_b32_e32 v149, v9, v21, vcc
	v_cndmask_b32_e32 v150, v10, v22, vcc
	v_cndmask_b32_e32 v151, v11, v23, vcc
	v_cndmask_b32_e64 v152, v8, v4, s[98:99]
	v_cndmask_b32_e64 v153, v9, v5, s[98:99]
	v_cndmask_b32_e64 v154, v10, v6, s[98:99]
	v_cndmask_b32_e64 v155, v11, v7, s[98:99]
	v_fma_f32 v237, v100, v8, v80
	v_fma_f32 v238, v101, v9, v81
	v_fma_f32 v239, v102, v10, v82
	v_fma_f32 v240, v103, v11, v83
	v_fmac_f32_dpp v237, v148, v112 row_ror:1 row_mask:0xf bank_mask:0xf
	v_fmac_f32_dpp v238, v149, v113 row_ror:1 row_mask:0xf bank_mask:0xf
	v_fmac_f32_dpp v239, v150, v114 row_ror:1 row_mask:0xf bank_mask:0xf
	v_fmac_f32_dpp v240, v151, v115 row_ror:1 row_mask:0xf bank_mask:0xf
	v_fmac_f32_dpp v237, v152, v92 row_ror:15 row_mask:0xf bank_mask:0xf
	v_fmac_f32_dpp v238, v153, v93 row_ror:15 row_mask:0xf bank_mask:0xf
	v_fmac_f32_dpp v239, v154, v94 row_ror:15 row_mask:0xf bank_mask:0xf
	v_fmac_f32_dpp v240, v155, v95 row_ror:15 row_mask:0xf bank_mask:0xf
	v_mul_f32_e32 v148, 0xbfb8aa3b, v156
	v_mul_f32_e32 v149, 0xbfb8aa3b, v157
	v_mul_f32_e32 v150, 0xbfb8aa3b, v158
	v_mul_f32_e32 v151, 0xbfb8aa3b, v159
	v_exp_f32_e32 v148, v148
	v_exp_f32_e32 v149, v149
	v_exp_f32_e32 v150, v150
	v_exp_f32_e32 v151, v151
	v_add_f32_e32 v148, 1.0, v148
	v_add_f32_e32 v149, 1.0, v149
	v_add_f32_e32 v150, 1.0, v150
	v_add_f32_e32 v151, 1.0, v151
	v_rcp_f32_e32 v148, v148
	v_rcp_f32_e32 v149, v149
	v_rcp_f32_e32 v150, v150
	v_rcp_f32_e32 v151, v151
	v_mul_f32_e32 v156, v156, v148
	v_mul_f32_e32 v157, v157, v149
	v_mul_f32_e32 v158, v158, v150
	v_mul_f32_e32 v159, v159, v151
	v_mul_f32_e32 v156, v156, v237
	v_mul_f32_e32 v157, v157, v238
	v_mul_f32_e32 v158, v158, v239
	v_mul_f32_e32 v159, v159, v240
	v_cvt_pk_bf16_f32 v40, v156, v157
	v_cvt_pk_bf16_f32 v41, v158, v159
	v_bfi_b32 v18, v146, v72, v40
	v_bfi_b32 v19, v146, v73, v41
	ds_swizzle_b32 v16, v18 offset:0x401f
	ds_swizzle_b32 v17, v19 offset:0x401f
	v_add_u32_e32 v42, 0xc6000, v250
	s_waitcnt lgkmcnt(0)
	v_bfi_b32 v148, v146, v16, v72
	v_bfi_b32 v149, v146, v17, v73
	v_bfi_b32 v150, v146, v40, v16
	v_bfi_b32 v151, v146, v41, v17
	global_store_dwordx4 v42, v[148:151], s[14:15]
	s_nop 1
	v_cndmask_b32_e32 v148, v24, v32, vcc
	v_cndmask_b32_e32 v149, v25, v33, vcc
	v_cndmask_b32_e32 v150, v26, v34, vcc
	v_cndmask_b32_e32 v151, v27, v35, vcc
	v_cndmask_b32_e64 v152, v24, v12, s[98:99]
	v_cndmask_b32_e64 v153, v25, v13, s[98:99]
	v_cndmask_b32_e64 v154, v26, v14, s[98:99]
	v_cndmask_b32_e64 v155, v27, v15, s[98:99]
	v_fma_f32 v156, v120, v24, v104
	v_fma_f32 v157, v121, v25, v105
	v_fma_f32 v158, v122, v26, v106
	v_fma_f32 v159, v123, v27, v107
	v_fmac_f32_dpp v156, v148, v124 row_ror:1 row_mask:0xf bank_mask:0xf
	v_fmac_f32_dpp v157, v149, v125 row_ror:1 row_mask:0xf bank_mask:0xf
	v_fmac_f32_dpp v158, v150, v126 row_ror:1 row_mask:0xf bank_mask:0xf
	v_fmac_f32_dpp v159, v151, v127 row_ror:1 row_mask:0xf bank_mask:0xf
	v_fmac_f32_dpp v156, v152, v116 row_ror:15 row_mask:0xf bank_mask:0xf
	v_fmac_f32_dpp v157, v153, v117 row_ror:15 row_mask:0xf bank_mask:0xf
	v_fmac_f32_dpp v158, v154, v118 row_ror:15 row_mask:0xf bank_mask:0xf
	v_fmac_f32_dpp v159, v155, v119 row_ror:15 row_mask:0xf bank_mask:0xf
	v_cndmask_b32_e32 v148, v4, v8, vcc
	v_cndmask_b32_e32 v149, v5, v9, vcc
	v_cndmask_b32_e32 v150, v6, v10, vcc
	v_cndmask_b32_e32 v151, v7, v11, vcc
	v_cndmask_b32_e64 v152, v4, v0, s[98:99]
	v_cndmask_b32_e64 v153, v5, v1, s[98:99]
	v_cndmask_b32_e64 v154, v6, v2, s[98:99]
	v_cndmask_b32_e64 v155, v7, v3, s[98:99]
	v_fma_f32 v237, v100, v4, v80
	v_fma_f32 v238, v101, v5, v81
	v_fma_f32 v239, v102, v6, v82
	v_fma_f32 v240, v103, v7, v83
	v_fmac_f32_dpp v237, v148, v112 row_ror:1 row_mask:0xf bank_mask:0xf
	v_fmac_f32_dpp v238, v149, v113 row_ror:1 row_mask:0xf bank_mask:0xf
	v_fmac_f32_dpp v239, v150, v114 row_ror:1 row_mask:0xf bank_mask:0xf
	v_fmac_f32_dpp v240, v151, v115 row_ror:1 row_mask:0xf bank_mask:0xf
	v_fmac_f32_dpp v237, v152, v92 row_ror:15 row_mask:0xf bank_mask:0xf
	v_fmac_f32_dpp v238, v153, v93 row_ror:15 row_mask:0xf bank_mask:0xf
	v_fmac_f32_dpp v239, v154, v94 row_ror:15 row_mask:0xf bank_mask:0xf
	v_fmac_f32_dpp v240, v155, v95 row_ror:15 row_mask:0xf bank_mask:0xf
	v_mul_f32_e32 v148, 0xbfb8aa3b, v156
	v_mul_f32_e32 v149, 0xbfb8aa3b, v157
	v_mul_f32_e32 v150, 0xbfb8aa3b, v158
	v_mul_f32_e32 v151, 0xbfb8aa3b, v159
	v_exp_f32_e32 v148, v148
	v_exp_f32_e32 v149, v149
	v_exp_f32_e32 v150, v150
	v_exp_f32_e32 v151, v151
	v_add_f32_e32 v148, 1.0, v148
	v_add_f32_e32 v149, 1.0, v149
	v_add_f32_e32 v150, 1.0, v150
	v_add_f32_e32 v151, 1.0, v151
	v_rcp_f32_e32 v148, v148
	v_rcp_f32_e32 v149, v149
	v_rcp_f32_e32 v150, v150
	v_rcp_f32_e32 v151, v151
	v_mul_f32_e32 v156, v156, v148
	v_mul_f32_e32 v157, v157, v149
	v_mul_f32_e32 v158, v158, v150
	v_mul_f32_e32 v159, v159, v151
	v_mul_f32_e32 v156, v156, v237
	v_mul_f32_e32 v157, v157, v238
	v_mul_f32_e32 v158, v158, v239
	v_mul_f32_e32 v159, v159, v240
	v_cvt_pk_bf16_f32 v40, v156, v157
	v_cvt_pk_bf16_f32 v41, v158, v159
	v_bfi_b32 v18, v146, v74, v40
	v_bfi_b32 v19, v146, v75, v41
	ds_swizzle_b32 v16, v18 offset:0x401f
	ds_swizzle_b32 v17, v19 offset:0x401f
	v_add_u32_e32 v42, 0xdc000, v250
	s_waitcnt lgkmcnt(0)
	v_bfi_b32 v148, v146, v16, v74
	v_bfi_b32 v149, v146, v17, v75
	v_bfi_b32 v150, v146, v40, v16
	v_bfi_b32 v151, v146, v41, v17
	global_store_dwordx4 v42, v[148:151], s[14:15]
	s_nop 1
	s_waitcnt lgkmcnt(0)
	v_cndmask_b32_e32 v148, v12, v24, vcc
	v_cndmask_b32_e32 v149, v13, v25, vcc
	v_cndmask_b32_e32 v150, v14, v26, vcc
	v_cndmask_b32_e32 v151, v15, v27, vcc
	v_cndmask_b32_e64 v152, v12, v160, s[98:99]
	v_cndmask_b32_e64 v153, v13, v161, s[98:99]
	v_cndmask_b32_e64 v154, v14, v162, s[98:99]
	v_cndmask_b32_e64 v155, v15, v163, s[98:99]
	v_fma_f32 v156, v120, v12, v104
	v_fma_f32 v157, v121, v13, v105
	v_fma_f32 v158, v122, v14, v106
	v_fma_f32 v159, v123, v15, v107
	v_fmac_f32_dpp v156, v148, v124 row_ror:1 row_mask:0xf bank_mask:0xf
	v_fmac_f32_dpp v157, v149, v125 row_ror:1 row_mask:0xf bank_mask:0xf
	v_fmac_f32_dpp v158, v150, v126 row_ror:1 row_mask:0xf bank_mask:0xf
	v_fmac_f32_dpp v159, v151, v127 row_ror:1 row_mask:0xf bank_mask:0xf
	v_fmac_f32_dpp v156, v152, v116 row_ror:15 row_mask:0xf bank_mask:0xf
	v_fmac_f32_dpp v157, v153, v117 row_ror:15 row_mask:0xf bank_mask:0xf
	v_fmac_f32_dpp v158, v154, v118 row_ror:15 row_mask:0xf bank_mask:0xf
	v_fmac_f32_dpp v159, v155, v119 row_ror:15 row_mask:0xf bank_mask:0xf
	v_cndmask_b32_e32 v148, v0, v4, vcc
	v_cndmask_b32_e32 v149, v1, v5, vcc
	v_cndmask_b32_e32 v150, v2, v6, vcc
	v_cndmask_b32_e32 v151, v3, v7, vcc
	v_cndmask_b32_e64 v152, v0, v164, s[98:99]
	v_cndmask_b32_e64 v153, v1, v165, s[98:99]
	v_cndmask_b32_e64 v154, v2, v166, s[98:99]
	v_cndmask_b32_e64 v155, v3, v167, s[98:99]
	v_fma_f32 v237, v100, v0, v80
	v_fma_f32 v238, v101, v1, v81
	v_fma_f32 v239, v102, v2, v82
	v_fma_f32 v240, v103, v3, v83
	v_fmac_f32_dpp v237, v148, v112 row_ror:1 row_mask:0xf bank_mask:0xf
	v_fmac_f32_dpp v238, v149, v113 row_ror:1 row_mask:0xf bank_mask:0xf
	v_fmac_f32_dpp v239, v150, v114 row_ror:1 row_mask:0xf bank_mask:0xf
	v_fmac_f32_dpp v240, v151, v115 row_ror:1 row_mask:0xf bank_mask:0xf
	v_fmac_f32_dpp v237, v152, v92 row_ror:15 row_mask:0xf bank_mask:0xf
	v_fmac_f32_dpp v238, v153, v93 row_ror:15 row_mask:0xf bank_mask:0xf
	v_fmac_f32_dpp v239, v154, v94 row_ror:15 row_mask:0xf bank_mask:0xf
	v_fmac_f32_dpp v240, v155, v95 row_ror:15 row_mask:0xf bank_mask:0xf
	v_mul_f32_e32 v148, 0xbfb8aa3b, v156
	v_mul_f32_e32 v149, 0xbfb8aa3b, v157
	v_mul_f32_e32 v150, 0xbfb8aa3b, v158
	v_mul_f32_e32 v151, 0xbfb8aa3b, v159
	v_exp_f32_e32 v148, v148
	v_exp_f32_e32 v149, v149
	v_exp_f32_e32 v150, v150
	v_exp_f32_e32 v151, v151
	v_add_f32_e32 v148, 1.0, v148
	v_add_f32_e32 v149, 1.0, v149
	v_add_f32_e32 v150, 1.0, v150
	v_add_f32_e32 v151, 1.0, v151
	v_rcp_f32_e32 v148, v148
	v_rcp_f32_e32 v149, v149
	v_rcp_f32_e32 v150, v150
	v_rcp_f32_e32 v151, v151
	v_mul_f32_e32 v156, v156, v148
	v_mul_f32_e32 v157, v157, v149
	v_mul_f32_e32 v158, v158, v150
	v_mul_f32_e32 v159, v159, v151
	v_mul_f32_e32 v156, v156, v237
	v_mul_f32_e32 v157, v157, v238
	v_mul_f32_e32 v158, v158, v239
	v_mul_f32_e32 v159, v159, v240
	v_cvt_pk_bf16_f32 v40, v156, v157
	v_cvt_pk_bf16_f32 v41, v158, v159
	v_bfi_b32 v18, v146, v48, v40
	v_bfi_b32 v19, v146, v49, v41
	ds_swizzle_b32 v16, v18 offset:0x401f
	ds_swizzle_b32 v17, v19 offset:0x401f
	v_add_u32_e32 v42, 0xf2000, v250
	v_lshrrev_b32_e32 v152, 6, v251
	s_nop 1
	v_readfirstlane_b32 s100, v152
	s_waitcnt lgkmcnt(0)
	v_bfi_b32 v148, v146, v16, v48
	v_bfi_b32 v149, v146, v17, v49
	v_bfi_b32 v150, v146, v40, v16
	v_bfi_b32 v151, v146, v41, v17
	s_cmp_eq_u32 s100, 1
	s_cselect_b64 s[100:101], vcc, 0
	s_andn2_b64 exec, exec, s[100:101]
	global_store_dwordx4 v42, v[148:151], s[14:15]
	s_mov_b64 exec, -1
	s_nop 1
	s_branch .LBB0_1215

.Lupf_u1_entry:
	v_mbcnt_lo_u32_b32 v253, -1, 0
	v_mbcnt_hi_u32_b32 v253, -1, v253
	v_and_b32_e32 v254, 15, v253
	v_lshrrev_b32_e32 v255, 4, v253
	s_lshr_b32 s100, s33, 6
	s_lshr_b32 s101, s100, 2
	s_and_b32 s100, s100, 3
	s_lshl_b32 vcc_lo, s101, 6
	v_add_u32_e32 v251, vcc_lo, v254
	s_add_i32 vcc_hi, s98, -1
	v_add_u32_e32 v250, vcc_hi, v251
	v_mul_u32_u24_e32 v250, 0x1600, v250
	s_lshl_b32 vcc_lo, s40, 7
	s_lshl_b32 vcc_hi, s100, 5
	s_add_i32 vcc_lo, vcc_lo, vcc_hi
	v_lshl_add_u32 v253, v255, 2, vcc_lo
	v_and_b32_e32 v252, 1, v255
	v_lshlrev_b32_e32 v252, 1, v252
	v_lshrrev_b32_e32 v245, 1, v255
	v_or_b32_e32 v252, v252, v245
	v_lshl_add_u32 v252, v252, 3, vcc_lo
	v_lshl_add_u32 v250, v252, 1, v250
	v_lshlrev_b32_e32 v146, 2, v253
	v_add_u32_e32 v147, 0x5800, v146
	v_add_u32_e32 v168, 0xb000, v146
	v_add_u32_e32 v169, 0x2c00, v146
	v_add_u32_e32 v245, 0x8400, v146
	v_add_u32_e32 v252, 0xdc00, v146
	global_load_dwordx4 v[172:175], v146, s[14:15] offset:0
	global_load_dwordx4 v[176:179], v147, s[14:15] offset:0
	global_load_dwordx4 v[180:183], v168, s[14:15] offset:0
	global_load_dwordx4 v[188:191], v169, s[14:15] offset:0
	global_load_dwordx4 v[192:195], v245, s[14:15] offset:0
	global_load_dwordx4 v[196:199], v252, s[14:15] offset:0
	global_load_dwordx4 v[184:187], v146, s[16:17] offset:0
	global_load_dwordx4 v[200:203], v169, s[16:17] offset:0
	s_lshl_b32 s101, s101, 11
	s_lshl_b32 s100, s100, 7
	s_add_i32 s101, s101, s100
	s_add_i32 s101, s101, 0x20000
	v_lshl_add_u32 v249, v255, 4, s101
	v_add_u32_e32 v253, 0x400, v249
	v_cmp_eq_u32_e64 s[98:99], 0, v254
	v_cmp_eq_u32_e32 vcc, 15, v254
	s_nop 4
	s_mov_b64 exec, s[98:99]
	ds_write_b128 v253, v[124:127] offset:0
	ds_write_b128 v253, v[108:111] offset:64
	ds_write_b128 v253, v[112:115] offset:512
	ds_write_b128 v253, v[84:87] offset:576
	ds_write_b128 v253, v[72:75] offset:4096
	ds_write_b128 v253, v[44:47] offset:4160
	ds_write_b128 v253, v[48:51] offset:4608
	ds_write_b128 v253, v[20:23] offset:4672
	s_mov_b64 exec, vcc
	ds_write_b128 v253, v[104:107] offset:1024
	ds_write_b128 v253, v[76:79] offset:1088
	ds_write_b128 v253, v[80:83] offset:1536
	ds_write_b128 v253, v[52:55] offset:1600
	ds_write_b128 v253, v[40:43] offset:5120
	ds_write_b128 v253, v[12:15] offset:5184
	ds_write_b128 v253, v[16:19] offset:5632
	ds_write_b128 v253, v[0:3] offset:5696
	s_mov_b64 exec, -1
	s_waitcnt lgkmcnt(0)
	s_barrier
	ds_read_b128 v[204:207], v249 offset:0
	ds_read_b128 v[208:211], v249 offset:512
	ds_read_b128 v[160:163], v249 offset:3072
	ds_read_b128 v[164:167], v249 offset:3584
	s_waitcnt vmcnt(0) lgkmcnt(0)
	v_cndmask_b32_e32 v148, v124, v204, vcc
	v_cndmask_b32_e32 v149, v125, v205, vcc
	v_cndmask_b32_e32 v150, v126, v206, vcc
	v_cndmask_b32_e32 v151, v127, v207, vcc
	v_cndmask_b32_e64 v152, v124, v120, s[98:99]
	v_cndmask_b32_e64 v153, v125, v121, s[98:99]
	v_cndmask_b32_e64 v154, v126, v122, s[98:99]
	v_cndmask_b32_e64 v155, v127, v123, s[98:99]
	v_fma_f32 v156, v176, v124, v184
	v_fma_f32 v157, v177, v125, v185
	v_fma_f32 v158, v178, v126, v186
	v_fma_f32 v159, v179, v127, v187
	v_fmac_f32_dpp v156, v148, v172 row_ror:1 row_mask:0xf bank_mask:0xf
	v_fmac_f32_dpp v157, v149, v173 row_ror:1 row_mask:0xf bank_mask:0xf
	v_fmac_f32_dpp v158, v150, v174 row_ror:1 row_mask:0xf bank_mask:0xf
	v_fmac_f32_dpp v159, v151, v175 row_ror:1 row_mask:0xf bank_mask:0xf
	v_fmac_f32_dpp v156, v152, v180 row_ror:15 row_mask:0xf bank_mask:0xf
	v_fmac_f32_dpp v157, v153, v181 row_ror:15 row_mask:0xf bank_mask:0xf
	v_fmac_f32_dpp v158, v154, v182 row_ror:15 row_mask:0xf bank_mask:0xf
	v_fmac_f32_dpp v159, v155, v183 row_ror:15 row_mask:0xf bank_mask:0xf
	v_cndmask_b32_e32 v148, v112, v208, vcc
	v_cndmask_b32_e32 v149, v113, v209, vcc
	v_cndmask_b32_e32 v150, v114, v210, vcc
	v_cndmask_b32_e32 v151, v115, v211, vcc
	v_cndmask_b32_e64 v152, v112, v100, s[98:99]
	v_cndmask_b32_e64 v153, v113, v101, s[98:99]
	v_cndmask_b32_e64 v154, v114, v102, s[98:99]
	v_cndmask_b32_e64 v155, v115, v103, s[98:99]
	v_fma_f32 v237, v192, v112, v200
	v_fma_f32 v238, v193, v113, v201
	v_fma_f32 v239, v194, v114, v202
	v_fma_f32 v240, v195, v115, v203
	v_fmac_f32_dpp v237, v148, v188 row_ror:1 row_mask:0xf bank_mask:0xf
	v_fmac_f32_dpp v238, v149, v189 row_ror:1 row_mask:0xf bank_mask:0xf
	v_fmac_f32_dpp v239, v150, v190 row_ror:1 row_mask:0xf bank_mask:0xf
	v_fmac_f32_dpp v240, v151, v191 row_ror:1 row_mask:0xf bank_mask:0xf
	v_fmac_f32_dpp v237, v152, v196 row_ror:15 row_mask:0xf bank_mask:0xf
	v_fmac_f32_dpp v238, v153, v197 row_ror:15 row_mask:0xf bank_mask:0xf
	v_fmac_f32_dpp v239, v154, v198 row_ror:15 row_mask:0xf bank_mask:0xf
	v_fmac_f32_dpp v240, v155, v199 row_ror:15 row_mask:0xf bank_mask:0xf
	v_mul_f32_e32 v148, 0xbfb8aa3b, v156
	v_mul_f32_e32 v149, 0xbfb8aa3b, v157
	v_mul_f32_e32 v150, 0xbfb8aa3b, v158
	v_mul_f32_e32 v151, 0xbfb8aa3b, v159
	v_exp_f32_e32 v148, v148
	v_exp_f32_e32 v149, v149
	v_exp_f32_e32 v150, v150
	v_exp_f32_e32 v151, v151
	v_add_f32_e32 v148, 1.0, v148
	v_add_f32_e32 v149, 1.0, v149
	v_add_f32_e32 v150, 1.0, v150
	v_add_f32_e32 v151, 1.0, v151
	v_rcp_f32_e32 v148, v148
	v_rcp_f32_e32 v149, v149
	v_rcp_f32_e32 v150, v150
	v_rcp_f32_e32 v151, v151
	v_mul_f32_e32 v156, v156, v148
	v_mul_f32_e32 v157, v157, v149
	v_mul_f32_e32 v158, v158, v150
	v_mul_f32_e32 v159, v159, v151
	v_mul_f32_e32 v156, v156, v237
	v_mul_f32_e32 v157, v157, v238
	v_mul_f32_e32 v158, v158, v239
	v_mul_f32_e32 v159, v159, v240
	v_cvt_pk_bf16_f32 v241, v156, v157
	v_cvt_pk_bf16_f32 v242, v158, v159
	ds_read_b128 v[204:207], v249 offset:4096
	ds_read_b128 v[208:211], v249 offset:4608
	v_cndmask_b32_e32 v148, v120, v124, vcc
	v_cndmask_b32_e32 v149, v121, v125, vcc
	v_cndmask_b32_e32 v150, v122, v126, vcc
	v_cndmask_b32_e32 v151, v123, v127, vcc
	v_cndmask_b32_e64 v152, v120, v116, s[98:99]
	v_cndmask_b32_e64 v153, v121, v117, s[98:99]
	v_cndmask_b32_e64 v154, v122, v118, s[98:99]
	v_cndmask_b32_e64 v155, v123, v119, s[98:99]
	v_fma_f32 v156, v176, v120, v184
	v_fma_f32 v157, v177, v121, v185
	v_fma_f32 v158, v178, v122, v186
	v_fma_f32 v159, v179, v123, v187
	v_fmac_f32_dpp v156, v148, v172 row_ror:1 row_mask:0xf bank_mask:0xf
	v_fmac_f32_dpp v157, v149, v173 row_ror:1 row_mask:0xf bank_mask:0xf
	v_fmac_f32_dpp v158, v150, v174 row_ror:1 row_mask:0xf bank_mask:0xf
	v_fmac_f32_dpp v159, v151, v175 row_ror:1 row_mask:0xf bank_mask:0xf
	v_fmac_f32_dpp v156, v152, v180 row_ror:15 row_mask:0xf bank_mask:0xf
	v_fmac_f32_dpp v157, v153, v181 row_ror:15 row_mask:0xf bank_mask:0xf
	v_fmac_f32_dpp v158, v154, v182 row_ror:15 row_mask:0xf bank_mask:0xf
	v_fmac_f32_dpp v159, v155, v183 row_ror:15 row_mask:0xf bank_mask:0xf
	v_cndmask_b32_e32 v148, v100, v112, vcc
	v_cndmask_b32_e32 v149, v101, v113, vcc
	v_cndmask_b32_e32 v150, v102, v114, vcc
	v_cndmask_b32_e32 v151, v103, v115, vcc
	v_cndmask_b32_e64 v152, v100, v92, s[98:99]
	v_cndmask_b32_e64 v153, v101, v93, s[98:99]
	v_cndmask_b32_e64 v154, v102, v94, s[98:99]
	v_cndmask_b32_e64 v155, v103, v95, s[98:99]
	v_fma_f32 v237, v192, v100, v200
	v_fma_f32 v238, v193, v101, v201
	v_fma_f32 v239, v194, v102, v202
	v_fma_f32 v240, v195, v103, v203
	v_fmac_f32_dpp v237, v148, v188 row_ror:1 row_mask:0xf bank_mask:0xf
	v_fmac_f32_dpp v238, v149, v189 row_ror:1 row_mask:0xf bank_mask:0xf
	v_fmac_f32_dpp v239, v150, v190 row_ror:1 row_mask:0xf bank_mask:0xf
	v_fmac_f32_dpp v240, v151, v191 row_ror:1 row_mask:0xf bank_mask:0xf
	v_fmac_f32_dpp v237, v152, v196 row_ror:15 row_mask:0xf bank_mask:0xf
	v_fmac_f32_dpp v238, v153, v197 row_ror:15 row_mask:0xf bank_mask:0xf
	v_fmac_f32_dpp v239, v154, v198 row_ror:15 row_mask:0xf bank_mask:0xf
	v_fmac_f32_dpp v240, v155, v199 row_ror:15 row_mask:0xf bank_mask:0xf
	v_mul_f32_e32 v148, 0xbfb8aa3b, v156
	v_mul_f32_e32 v149, 0xbfb8aa3b, v157
	v_mul_f32_e32 v150, 0xbfb8aa3b, v158
	v_mul_f32_e32 v151, 0xbfb8aa3b, v159
	v_exp_f32_e32 v148, v148
	v_exp_f32_e32 v149, v149
	v_exp_f32_e32 v150, v150
	v_exp_f32_e32 v151, v151
	v_add_f32_e32 v148, 1.0, v148
	v_add_f32_e32 v149, 1.0, v149
	v_add_f32_e32 v150, 1.0, v150
	v_add_f32_e32 v151, 1.0, v151
	v_rcp_f32_e32 v148, v148
	v_rcp_f32_e32 v149, v149
	v_rcp_f32_e32 v150, v150
	v_rcp_f32_e32 v151, v151
	v_mul_f32_e32 v156, v156, v148
	v_mul_f32_e32 v157, v157, v149
	v_mul_f32_e32 v158, v158, v150
	v_mul_f32_e32 v159, v159, v151
	v_mul_f32_e32 v156, v156, v237
	v_mul_f32_e32 v157, v157, v238
	v_mul_f32_e32 v158, v158, v239
	v_mul_f32_e32 v159, v159, v240
	v_cvt_pk_bf16_f32 v243, v156, v157
	v_cvt_pk_bf16_f32 v244, v158, v159
	v_cndmask_b32_e32 v148, v116, v120, vcc
	v_cndmask_b32_e32 v149, v117, v121, vcc
	v_cndmask_b32_e32 v150, v118, v122, vcc
	v_cndmask_b32_e32 v151, v119, v123, vcc
	v_cndmask_b32_e64 v152, v116, v104, s[98:99]
	v_cndmask_b32_e64 v153, v117, v105, s[98:99]
	v_cndmask_b32_e64 v154, v118, v106, s[98:99]
	v_cndmask_b32_e64 v155, v119, v107, s[98:99]
	v_fma_f32 v156, v176, v116, v184
	v_fma_f32 v157, v177, v117, v185
	v_fma_f32 v158, v178, v118, v186
	v_fma_f32 v159, v179, v119, v187
	v_fmac_f32_dpp v156, v148, v172 row_ror:1 row_mask:0xf bank_mask:0xf
	v_fmac_f32_dpp v157, v149, v173 row_ror:1 row_mask:0xf bank_mask:0xf
	v_fmac_f32_dpp v158, v150, v174 row_ror:1 row_mask:0xf bank_mask:0xf
	v_fmac_f32_dpp v159, v151, v175 row_ror:1 row_mask:0xf bank_mask:0xf
	v_fmac_f32_dpp v156, v152, v180 row_ror:15 row_mask:0xf bank_mask:0xf
	v_fmac_f32_dpp v157, v153, v181 row_ror:15 row_mask:0xf bank_mask:0xf
	v_fmac_f32_dpp v158, v154, v182 row_ror:15 row_mask:0xf bank_mask:0xf
	v_fmac_f32_dpp v159, v155, v183 row_ror:15 row_mask:0xf bank_mask:0xf
	v_cndmask_b32_e32 v148, v92, v100, vcc
	v_cndmask_b32_e32 v149, v93, v101, vcc
	v_cndmask_b32_e32 v150, v94, v102, vcc
	v_cndmask_b32_e32 v151, v95, v103, vcc
	v_cndmask_b32_e64 v152, v92, v80, s[98:99]
	v_cndmask_b32_e64 v153, v93, v81, s[98:99]
	v_cndmask_b32_e64 v154, v94, v82, s[98:99]
	v_cndmask_b32_e64 v155, v95, v83, s[98:99]
	v_fma_f32 v237, v192, v92, v200
	v_fma_f32 v238, v193, v93, v201
	v_fma_f32 v239, v194, v94, v202
	v_fma_f32 v240, v195, v95, v203
	v_fmac_f32_dpp v237, v148, v188 row_ror:1 row_mask:0xf bank_mask:0xf
	v_fmac_f32_dpp v238, v149, v189 row_ror:1 row_mask:0xf bank_mask:0xf
	v_fmac_f32_dpp v239, v150, v190 row_ror:1 row_mask:0xf bank_mask:0xf
	v_fmac_f32_dpp v240, v151, v191 row_ror:1 row_mask:0xf bank_mask:0xf
	v_fmac_f32_dpp v237, v152, v196 row_ror:15 row_mask:0xf bank_mask:0xf
	v_fmac_f32_dpp v238, v153, v197 row_ror:15 row_mask:0xf bank_mask:0xf
	v_fmac_f32_dpp v239, v154, v198 row_ror:15 row_mask:0xf bank_mask:0xf
	v_fmac_f32_dpp v240, v155, v199 row_ror:15 row_mask:0xf bank_mask:0xf
	v_mul_f32_e32 v148, 0xbfb8aa3b, v156
	v_mul_f32_e32 v149, 0xbfb8aa3b, v157
	v_mul_f32_e32 v150, 0xbfb8aa3b, v158
	v_mul_f32_e32 v151, 0xbfb8aa3b, v159
	v_exp_f32_e32 v148, v148
	v_exp_f32_e32 v149, v149
	v_exp_f32_e32 v150, v150
	v_exp_f32_e32 v151, v151
	v_add_f32_e32 v148, 1.0, v148
	v_add_f32_e32 v149, 1.0, v149
	v_add_f32_e32 v150, 1.0, v150
	v_add_f32_e32 v151, 1.0, v151
	v_rcp_f32_e32 v148, v148
	v_rcp_f32_e32 v149, v149
	v_rcp_f32_e32 v150, v150
	v_rcp_f32_e32 v151, v151
	v_mul_f32_e32 v156, v156, v148
	v_mul_f32_e32 v157, v157, v149
	v_mul_f32_e32 v158, v158, v150
	v_mul_f32_e32 v159, v159, v151
	v_mul_f32_e32 v156, v156, v237
	v_mul_f32_e32 v157, v157, v238
	v_mul_f32_e32 v158, v158, v239
	v_mul_f32_e32 v159, v159, v240
	v_cvt_pk_bf16_f32 v253, v156, v157
	v_cvt_pk_bf16_f32 v254, v158, v159
	v_cndmask_b32_e32 v148, v104, v116, vcc
	v_cndmask_b32_e32 v149, v105, v117, vcc
	v_cndmask_b32_e32 v150, v106, v118, vcc
	v_cndmask_b32_e32 v151, v107, v119, vcc
	v_cndmask_b32_e64 v152, v104, v160, s[98:99]
	v_cndmask_b32_e64 v153, v105, v161, s[98:99]
	v_cndmask_b32_e64 v154, v106, v162, s[98:99]
	v_cndmask_b32_e64 v155, v107, v163, s[98:99]
	v_fma_f32 v156, v176, v104, v184
	v_fma_f32 v157, v177, v105, v185
	v_fma_f32 v158, v178, v106, v186
	v_fma_f32 v159, v179, v107, v187
	v_fmac_f32_dpp v156, v148, v172 row_ror:1 row_mask:0xf bank_mask:0xf
	v_fmac_f32_dpp v157, v149, v173 row_ror:1 row_mask:0xf bank_mask:0xf
	v_fmac_f32_dpp v158, v150, v174 row_ror:1 row_mask:0xf bank_mask:0xf
	v_fmac_f32_dpp v159, v151, v175 row_ror:1 row_mask:0xf bank_mask:0xf
	v_fmac_f32_dpp v156, v152, v180 row_ror:15 row_mask:0xf bank_mask:0xf
	v_fmac_f32_dpp v157, v153, v181 row_ror:15 row_mask:0xf bank_mask:0xf
	v_fmac_f32_dpp v158, v154, v182 row_ror:15 row_mask:0xf bank_mask:0xf
	v_fmac_f32_dpp v159, v155, v183 row_ror:15 row_mask:0xf bank_mask:0xf
	v_cndmask_b32_e32 v148, v80, v92, vcc
	v_cndmask_b32_e32 v149, v81, v93, vcc
	v_cndmask_b32_e32 v150, v82, v94, vcc
	v_cndmask_b32_e32 v151, v83, v95, vcc
	v_cndmask_b32_e64 v152, v80, v164, s[98:99]
	v_cndmask_b32_e64 v153, v81, v165, s[98:99]
	v_cndmask_b32_e64 v154, v82, v166, s[98:99]
	v_cndmask_b32_e64 v155, v83, v167, s[98:99]
	v_fma_f32 v237, v192, v80, v200
	v_fma_f32 v238, v193, v81, v201
	v_fma_f32 v239, v194, v82, v202
	v_fma_f32 v240, v195, v83, v203
	v_fmac_f32_dpp v237, v148, v188 row_ror:1 row_mask:0xf bank_mask:0xf
	v_fmac_f32_dpp v238, v149, v189 row_ror:1 row_mask:0xf bank_mask:0xf
	v_fmac_f32_dpp v239, v150, v190 row_ror:1 row_mask:0xf bank_mask:0xf
	v_fmac_f32_dpp v240, v151, v191 row_ror:1 row_mask:0xf bank_mask:0xf
	v_fmac_f32_dpp v237, v152, v196 row_ror:15 row_mask:0xf bank_mask:0xf
	v_fmac_f32_dpp v238, v153, v197 row_ror:15 row_mask:0xf bank_mask:0xf
	v_fmac_f32_dpp v239, v154, v198 row_ror:15 row_mask:0xf bank_mask:0xf
	v_fmac_f32_dpp v240, v155, v199 row_ror:15 row_mask:0xf bank_mask:0xf
	v_mul_f32_e32 v148, 0xbfb8aa3b, v156
	v_mul_f32_e32 v149, 0xbfb8aa3b, v157
	v_mul_f32_e32 v150, 0xbfb8aa3b, v158
	v_mul_f32_e32 v151, 0xbfb8aa3b, v159
	v_exp_f32_e32 v148, v148
	v_exp_f32_e32 v149, v149
	v_exp_f32_e32 v150, v150
	v_exp_f32_e32 v151, v151
	v_add_f32_e32 v148, 1.0, v148
	v_add_f32_e32 v149, 1.0, v149
	v_add_f32_e32 v150, 1.0, v150
	v_add_f32_e32 v151, 1.0, v151
	v_rcp_f32_e32 v148, v148
	v_rcp_f32_e32 v149, v149
	v_rcp_f32_e32 v150, v150
	v_rcp_f32_e32 v151, v151
	v_mul_f32_e32 v156, v156, v148
	v_mul_f32_e32 v157, v157, v149
	v_mul_f32_e32 v158, v158, v150
	v_mul_f32_e32 v159, v159, v151
	v_mul_f32_e32 v156, v156, v237
	v_mul_f32_e32 v157, v157, v238
	v_mul_f32_e32 v158, v158, v239
	v_mul_f32_e32 v159, v159, v240
	v_cvt_pk_bf16_f32 v255, v156, v157
	v_cvt_pk_bf16_f32 v246, v158, v159
	global_load_dwordx4 v[124:127], v146, s[14:15] offset:64
	global_load_dwordx4 v[120:123], v147, s[14:15] offset:64
	global_load_dwordx4 v[116:119], v168, s[14:15] offset:64
	global_load_dwordx4 v[112:115], v169, s[14:15] offset:64
	global_load_dwordx4 v[100:103], v245, s[14:15] offset:64
	global_load_dwordx4 v[92:95], v252, s[14:15] offset:64
	global_load_dwordx4 v[104:107], v146, s[16:17] offset:64
	global_load_dwordx4 v[80:83], v169, s[16:17] offset:64
	ds_read_b128 v[160:163], v249 offset:7168
	ds_read_b128 v[164:167], v249 offset:7680
	s_waitcnt lgkmcnt(2)
	v_cndmask_b32_e32 v148, v72, v204, vcc
	v_cndmask_b32_e32 v149, v73, v205, vcc
	v_cndmask_b32_e32 v150, v74, v206, vcc
	v_cndmask_b32_e32 v151, v75, v207, vcc
	v_cndmask_b32_e64 v152, v72, v64, s[98:99]
	v_cndmask_b32_e64 v153, v73, v65, s[98:99]
	v_cndmask_b32_e64 v154, v74, v66, s[98:99]
	v_cndmask_b32_e64 v155, v75, v67, s[98:99]
	v_fma_f32 v156, v176, v72, v184
	v_fma_f32 v157, v177, v73, v185
	v_fma_f32 v158, v178, v74, v186
	v_fma_f32 v159, v179, v75, v187
	v_fmac_f32_dpp v156, v148, v172 row_ror:1 row_mask:0xf bank_mask:0xf
	v_fmac_f32_dpp v157, v149, v173 row_ror:1 row_mask:0xf bank_mask:0xf
	v_fmac_f32_dpp v158, v150, v174 row_ror:1 row_mask:0xf bank_mask:0xf
	v_fmac_f32_dpp v159, v151, v175 row_ror:1 row_mask:0xf bank_mask:0xf
	v_fmac_f32_dpp v156, v152, v180 row_ror:15 row_mask:0xf bank_mask:0xf
	v_fmac_f32_dpp v157, v153, v181 row_ror:15 row_mask:0xf bank_mask:0xf
	v_fmac_f32_dpp v158, v154, v182 row_ror:15 row_mask:0xf bank_mask:0xf
	v_fmac_f32_dpp v159, v155, v183 row_ror:15 row_mask:0xf bank_mask:0xf
	v_cndmask_b32_e32 v148, v48, v208, vcc
	v_cndmask_b32_e32 v149, v49, v209, vcc
	v_cndmask_b32_e32 v150, v50, v210, vcc
	v_cndmask_b32_e32 v151, v51, v211, vcc
	v_cndmask_b32_e64 v152, v48, v36, s[98:99]
	v_cndmask_b32_e64 v153, v49, v37, s[98:99]
	v_cndmask_b32_e64 v154, v50, v38, s[98:99]
	v_cndmask_b32_e64 v155, v51, v39, s[98:99]
	v_fma_f32 v237, v192, v48, v200
	v_fma_f32 v238, v193, v49, v201
	v_fma_f32 v239, v194, v50, v202
	v_fma_f32 v240, v195, v51, v203
	v_fmac_f32_dpp v237, v148, v188 row_ror:1 row_mask:0xf bank_mask:0xf
	v_fmac_f32_dpp v238, v149, v189 row_ror:1 row_mask:0xf bank_mask:0xf
	v_fmac_f32_dpp v239, v150, v190 row_ror:1 row_mask:0xf bank_mask:0xf
	v_fmac_f32_dpp v240, v151, v191 row_ror:1 row_mask:0xf bank_mask:0xf
	v_fmac_f32_dpp v237, v152, v196 row_ror:15 row_mask:0xf bank_mask:0xf
	v_fmac_f32_dpp v238, v153, v197 row_ror:15 row_mask:0xf bank_mask:0xf
	v_fmac_f32_dpp v239, v154, v198 row_ror:15 row_mask:0xf bank_mask:0xf
	v_fmac_f32_dpp v240, v155, v199 row_ror:15 row_mask:0xf bank_mask:0xf
	v_mul_f32_e32 v148, 0xbfb8aa3b, v156
	v_mul_f32_e32 v149, 0xbfb8aa3b, v157
	v_mul_f32_e32 v150, 0xbfb8aa3b, v158
	v_mul_f32_e32 v151, 0xbfb8aa3b, v159
	v_exp_f32_e32 v148, v148
	v_exp_f32_e32 v149, v149
	v_exp_f32_e32 v150, v150
	v_exp_f32_e32 v151, v151
	v_add_f32_e32 v148, 1.0, v148
	v_add_f32_e32 v149, 1.0, v149
	v_add_f32_e32 v150, 1.0, v150
	v_add_f32_e32 v151, 1.0, v151
	v_rcp_f32_e32 v148, v148
	v_rcp_f32_e32 v149, v149
	v_rcp_f32_e32 v150, v150
	v_rcp_f32_e32 v151, v151
	v_mul_f32_e32 v156, v156, v148
	v_mul_f32_e32 v157, v157, v149
	v_mul_f32_e32 v158, v158, v150
	v_mul_f32_e32 v159, v159, v151
	v_mul_f32_e32 v156, v156, v237
	v_mul_f32_e32 v157, v157, v238
	v_mul_f32_e32 v158, v158, v239
	v_mul_f32_e32 v159, v159, v240
	v_cvt_pk_bf16_f32 v247, v156, v157
	v_cvt_pk_bf16_f32 v248, v158, v159
	ds_read_b128 v[204:207], v249 offset:64
	ds_read_b128 v[208:211], v249 offset:576
	v_cndmask_b32_e32 v148, v64, v72, vcc
	v_cndmask_b32_e32 v149, v65, v73, vcc
	v_cndmask_b32_e32 v150, v66, v74, vcc
	v_cndmask_b32_e32 v151, v67, v75, vcc
	v_cndmask_b32_e64 v152, v64, v56, s[98:99]
	v_cndmask_b32_e64 v153, v65, v57, s[98:99]
	v_cndmask_b32_e64 v154, v66, v58, s[98:99]
	v_cndmask_b32_e64 v155, v67, v59, s[98:99]
	v_fma_f32 v156, v176, v64, v184
	v_fma_f32 v157, v177, v65, v185
	v_fma_f32 v158, v178, v66, v186
	v_fma_f32 v159, v179, v67, v187
	v_fmac_f32_dpp v156, v148, v172 row_ror:1 row_mask:0xf bank_mask:0xf
	v_fmac_f32_dpp v157, v149, v173 row_ror:1 row_mask:0xf bank_mask:0xf
	v_fmac_f32_dpp v158, v150, v174 row_ror:1 row_mask:0xf bank_mask:0xf
	v_fmac_f32_dpp v159, v151, v175 row_ror:1 row_mask:0xf bank_mask:0xf
	v_fmac_f32_dpp v156, v152, v180 row_ror:15 row_mask:0xf bank_mask:0xf
	v_fmac_f32_dpp v157, v153, v181 row_ror:15 row_mask:0xf bank_mask:0xf
	v_fmac_f32_dpp v158, v154, v182 row_ror:15 row_mask:0xf bank_mask:0xf
	v_fmac_f32_dpp v159, v155, v183 row_ror:15 row_mask:0xf bank_mask:0xf
	v_cndmask_b32_e32 v148, v36, v48, vcc
	v_cndmask_b32_e32 v149, v37, v49, vcc
	v_cndmask_b32_e32 v150, v38, v50, vcc
	v_cndmask_b32_e32 v151, v39, v51, vcc
	v_cndmask_b32_e64 v152, v36, v28, s[98:99]
	v_cndmask_b32_e64 v153, v37, v29, s[98:99]
	v_cndmask_b32_e64 v154, v38, v30, s[98:99]
	v_cndmask_b32_e64 v155, v39, v31, s[98:99]
	v_fma_f32 v237, v192, v36, v200
	v_fma_f32 v238, v193, v37, v201
	v_fma_f32 v239, v194, v38, v202
	v_fma_f32 v240, v195, v39, v203
	v_fmac_f32_dpp v237, v148, v188 row_ror:1 row_mask:0xf bank_mask:0xf
	v_fmac_f32_dpp v238, v149, v189 row_ror:1 row_mask:0xf bank_mask:0xf
	v_fmac_f32_dpp v239, v150, v190 row_ror:1 row_mask:0xf bank_mask:0xf
	v_fmac_f32_dpp v240, v151, v191 row_ror:1 row_mask:0xf bank_mask:0xf
	v_fmac_f32_dpp v237, v152, v196 row_ror:15 row_mask:0xf bank_mask:0xf
	v_fmac_f32_dpp v238, v153, v197 row_ror:15 row_mask:0xf bank_mask:0xf
	v_fmac_f32_dpp v239, v154, v198 row_ror:15 row_mask:0xf bank_mask:0xf
	v_fmac_f32_dpp v240, v155, v199 row_ror:15 row_mask:0xf bank_mask:0xf
	v_mul_f32_e32 v148, 0xbfb8aa3b, v156
	v_mul_f32_e32 v149, 0xbfb8aa3b, v157
	v_mul_f32_e32 v150, 0xbfb8aa3b, v158
	v_mul_f32_e32 v151, 0xbfb8aa3b, v159
	v_exp_f32_e32 v148, v148
	v_exp_f32_e32 v149, v149
	v_exp_f32_e32 v150, v150
	v_exp_f32_e32 v151, v151
	v_add_f32_e32 v148, 1.0, v148
	v_add_f32_e32 v149, 1.0, v149
	v_add_f32_e32 v150, 1.0, v150
	v_add_f32_e32 v151, 1.0, v151
	v_rcp_f32_e32 v148, v148
	v_rcp_f32_e32 v149, v149
	v_rcp_f32_e32 v150, v150
	v_rcp_f32_e32 v151, v151
	v_mul_f32_e32 v156, v156, v148
	v_mul_f32_e32 v157, v157, v149
	v_mul_f32_e32 v158, v158, v150
	v_mul_f32_e32 v159, v159, v151
	v_mul_f32_e32 v156, v156, v237
	v_mul_f32_e32 v157, v157, v238
	v_mul_f32_e32 v158, v158, v239
	v_mul_f32_e32 v159, v159, v240
	v_cvt_pk_bf16_f32 v72, v156, v157
	v_cvt_pk_bf16_f32 v73, v158, v159
	v_cndmask_b32_e32 v148, v56, v64, vcc
	v_cndmask_b32_e32 v149, v57, v65, vcc
	v_cndmask_b32_e32 v150, v58, v66, vcc
	v_cndmask_b32_e32 v151, v59, v67, vcc
	v_cndmask_b32_e64 v152, v56, v40, s[98:99]
	v_cndmask_b32_e64 v153, v57, v41, s[98:99]
	v_cndmask_b32_e64 v154, v58, v42, s[98:99]
	v_cndmask_b32_e64 v155, v59, v43, s[98:99]
	v_fma_f32 v156, v176, v56, v184
	v_fma_f32 v157, v177, v57, v185
	v_fma_f32 v158, v178, v58, v186
	v_fma_f32 v159, v179, v59, v187
	v_fmac_f32_dpp v156, v148, v172 row_ror:1 row_mask:0xf bank_mask:0xf
	v_fmac_f32_dpp v157, v149, v173 row_ror:1 row_mask:0xf bank_mask:0xf
	v_fmac_f32_dpp v158, v150, v174 row_ror:1 row_mask:0xf bank_mask:0xf
	v_fmac_f32_dpp v159, v151, v175 row_ror:1 row_mask:0xf bank_mask:0xf
	v_fmac_f32_dpp v156, v152, v180 row_ror:15 row_mask:0xf bank_mask:0xf
	v_fmac_f32_dpp v157, v153, v181 row_ror:15 row_mask:0xf bank_mask:0xf
	v_fmac_f32_dpp v158, v154, v182 row_ror:15 row_mask:0xf bank_mask:0xf
	v_fmac_f32_dpp v159, v155, v183 row_ror:15 row_mask:0xf bank_mask:0xf
	v_cndmask_b32_e32 v148, v28, v36, vcc
	v_cndmask_b32_e32 v149, v29, v37, vcc
	v_cndmask_b32_e32 v150, v30, v38, vcc
	v_cndmask_b32_e32 v151, v31, v39, vcc
	v_cndmask_b32_e64 v152, v28, v16, s[98:99]
	v_cndmask_b32_e64 v153, v29, v17, s[98:99]
	v_cndmask_b32_e64 v154, v30, v18, s[98:99]
	v_cndmask_b32_e64 v155, v31, v19, s[98:99]
	v_fma_f32 v237, v192, v28, v200
	v_fma_f32 v238, v193, v29, v201
	v_fma_f32 v239, v194, v30, v202
	v_fma_f32 v240, v195, v31, v203
	v_fmac_f32_dpp v237, v148, v188 row_ror:1 row_mask:0xf bank_mask:0xf
	v_fmac_f32_dpp v238, v149, v189 row_ror:1 row_mask:0xf bank_mask:0xf
	v_fmac_f32_dpp v239, v150, v190 row_ror:1 row_mask:0xf bank_mask:0xf
	v_fmac_f32_dpp v240, v151, v191 row_ror:1 row_mask:0xf bank_mask:0xf
	v_fmac_f32_dpp v237, v152, v196 row_ror:15 row_mask:0xf bank_mask:0xf
	v_fmac_f32_dpp v238, v153, v197 row_ror:15 row_mask:0xf bank_mask:0xf
	v_fmac_f32_dpp v239, v154, v198 row_ror:15 row_mask:0xf bank_mask:0xf
	v_fmac_f32_dpp v240, v155, v199 row_ror:15 row_mask:0xf bank_mask:0xf
	v_mul_f32_e32 v148, 0xbfb8aa3b, v156
	v_mul_f32_e32 v149, 0xbfb8aa3b, v157
	v_mul_f32_e32 v150, 0xbfb8aa3b, v158
	v_mul_f32_e32 v151, 0xbfb8aa3b, v159
	v_exp_f32_e32 v148, v148
	v_exp_f32_e32 v149, v149
	v_exp_f32_e32 v150, v150
	v_exp_f32_e32 v151, v151
	v_add_f32_e32 v148, 1.0, v148
	v_add_f32_e32 v149, 1.0, v149
	v_add_f32_e32 v150, 1.0, v150
	v_add_f32_e32 v151, 1.0, v151
	v_rcp_f32_e32 v148, v148
	v_rcp_f32_e32 v149, v149
	v_rcp_f32_e32 v150, v150
	v_rcp_f32_e32 v151, v151
	v_mul_f32_e32 v156, v156, v148
	v_mul_f32_e32 v157, v157, v149
	v_mul_f32_e32 v158, v158, v150
	v_mul_f32_e32 v159, v159, v151
	v_mul_f32_e32 v156, v156, v237
	v_mul_f32_e32 v157, v157, v238
	v_mul_f32_e32 v158, v158, v239
	v_mul_f32_e32 v159, v159, v240
	v_cvt_pk_bf16_f32 v74, v156, v157
	v_cvt_pk_bf16_f32 v75, v158, v159
	s_waitcnt lgkmcnt(2)
	v_cndmask_b32_e32 v148, v40, v56, vcc
	v_cndmask_b32_e32 v149, v41, v57, vcc
	v_cndmask_b32_e32 v150, v42, v58, vcc
	v_cndmask_b32_e32 v151, v43, v59, vcc
	v_cndmask_b32_e64 v152, v40, v160, s[98:99]
	v_cndmask_b32_e64 v153, v41, v161, s[98:99]
	v_cndmask_b32_e64 v154, v42, v162, s[98:99]
	v_cndmask_b32_e64 v155, v43, v163, s[98:99]
	v_fma_f32 v156, v176, v40, v184
	v_fma_f32 v157, v177, v41, v185
	v_fma_f32 v158, v178, v42, v186
	v_fma_f32 v159, v179, v43, v187
	v_fmac_f32_dpp v156, v148, v172 row_ror:1 row_mask:0xf bank_mask:0xf
	v_fmac_f32_dpp v157, v149, v173 row_ror:1 row_mask:0xf bank_mask:0xf
	v_fmac_f32_dpp v158, v150, v174 row_ror:1 row_mask:0xf bank_mask:0xf
	v_fmac_f32_dpp v159, v151, v175 row_ror:1 row_mask:0xf bank_mask:0xf
	v_fmac_f32_dpp v156, v152, v180 row_ror:15 row_mask:0xf bank_mask:0xf
	v_fmac_f32_dpp v157, v153, v181 row_ror:15 row_mask:0xf bank_mask:0xf
	v_fmac_f32_dpp v158, v154, v182 row_ror:15 row_mask:0xf bank_mask:0xf
	v_fmac_f32_dpp v159, v155, v183 row_ror:15 row_mask:0xf bank_mask:0xf
	v_cndmask_b32_e32 v148, v16, v28, vcc
	v_cndmask_b32_e32 v149, v17, v29, vcc
	v_cndmask_b32_e32 v150, v18, v30, vcc
	v_cndmask_b32_e32 v151, v19, v31, vcc
	v_cndmask_b32_e64 v152, v16, v164, s[98:99]
	v_cndmask_b32_e64 v153, v17, v165, s[98:99]
	v_cndmask_b32_e64 v154, v18, v166, s[98:99]
	v_cndmask_b32_e64 v155, v19, v167, s[98:99]
	v_fma_f32 v237, v192, v16, v200
	v_fma_f32 v238, v193, v17, v201
	v_fma_f32 v239, v194, v18, v202
	v_fma_f32 v240, v195, v19, v203
	v_fmac_f32_dpp v237, v148, v188 row_ror:1 row_mask:0xf bank_mask:0xf
	v_fmac_f32_dpp v238, v149, v189 row_ror:1 row_mask:0xf bank_mask:0xf
	v_fmac_f32_dpp v239, v150, v190 row_ror:1 row_mask:0xf bank_mask:0xf
	v_fmac_f32_dpp v240, v151, v191 row_ror:1 row_mask:0xf bank_mask:0xf
	v_fmac_f32_dpp v237, v152, v196 row_ror:15 row_mask:0xf bank_mask:0xf
	v_fmac_f32_dpp v238, v153, v197 row_ror:15 row_mask:0xf bank_mask:0xf
	v_fmac_f32_dpp v239, v154, v198 row_ror:15 row_mask:0xf bank_mask:0xf
	v_fmac_f32_dpp v240, v155, v199 row_ror:15 row_mask:0xf bank_mask:0xf
	v_mul_f32_e32 v148, 0xbfb8aa3b, v156
	v_mul_f32_e32 v149, 0xbfb8aa3b, v157
	v_mul_f32_e32 v150, 0xbfb8aa3b, v158
	v_mul_f32_e32 v151, 0xbfb8aa3b, v159
	v_exp_f32_e32 v148, v148
	v_exp_f32_e32 v149, v149
	v_exp_f32_e32 v150, v150
	v_exp_f32_e32 v151, v151
	v_add_f32_e32 v148, 1.0, v148
	v_add_f32_e32 v149, 1.0, v149
	v_add_f32_e32 v150, 1.0, v150
	v_add_f32_e32 v151, 1.0, v151
	v_rcp_f32_e32 v148, v148
	v_rcp_f32_e32 v149, v149
	v_rcp_f32_e32 v150, v150
	v_rcp_f32_e32 v151, v151
	v_mul_f32_e32 v156, v156, v148
	v_mul_f32_e32 v157, v157, v149
	v_mul_f32_e32 v158, v158, v150
	v_mul_f32_e32 v159, v159, v151
	v_mul_f32_e32 v156, v156, v237
	v_mul_f32_e32 v157, v157, v238
	v_mul_f32_e32 v158, v158, v239
	v_mul_f32_e32 v159, v159, v240
	v_cvt_pk_bf16_f32 v48, v156, v157
	v_cvt_pk_bf16_f32 v49, v158, v159
	ds_read_b128 v[160:163], v249 offset:3136
	ds_read_b128 v[164:167], v249 offset:3648
	s_waitcnt vmcnt(0) lgkmcnt(0)
	v_mbcnt_lo_u32_b32 v146, -1, 0
	v_mbcnt_hi_u32_b32 v146, -1, v146
	v_bfe_i32 v146, v146, 4, 1
	v_cndmask_b32_e32 v148, v108, v204, vcc
	v_cndmask_b32_e32 v149, v109, v205, vcc
	v_cndmask_b32_e32 v150, v110, v206, vcc
	v_cndmask_b32_e32 v151, v111, v207, vcc
	v_cndmask_b32_e64 v152, v108, v96, s[98:99]
	v_cndmask_b32_e64 v153, v109, v97, s[98:99]
	v_cndmask_b32_e64 v154, v110, v98, s[98:99]
	v_cndmask_b32_e64 v155, v111, v99, s[98:99]
	v_fma_f32 v156, v120, v108, v104
	v_fma_f32 v157, v121, v109, v105
	v_fma_f32 v158, v122, v110, v106
	v_fma_f32 v159, v123, v111, v107
	v_fmac_f32_dpp v156, v148, v124 row_ror:1 row_mask:0xf bank_mask:0xf
	v_fmac_f32_dpp v157, v149, v125 row_ror:1 row_mask:0xf bank_mask:0xf
	v_fmac_f32_dpp v158, v150, v126 row_ror:1 row_mask:0xf bank_mask:0xf
	v_fmac_f32_dpp v159, v151, v127 row_ror:1 row_mask:0xf bank_mask:0xf
	v_fmac_f32_dpp v156, v152, v116 row_ror:15 row_mask:0xf bank_mask:0xf
	v_fmac_f32_dpp v157, v153, v117 row_ror:15 row_mask:0xf bank_mask:0xf
	v_fmac_f32_dpp v158, v154, v118 row_ror:15 row_mask:0xf bank_mask:0xf
	v_fmac_f32_dpp v159, v155, v119 row_ror:15 row_mask:0xf bank_mask:0xf
	v_cndmask_b32_e32 v148, v84, v208, vcc
	v_cndmask_b32_e32 v149, v85, v209, vcc
	v_cndmask_b32_e32 v150, v86, v210, vcc
	v_cndmask_b32_e32 v151, v87, v211, vcc
	v_cndmask_b32_e64 v152, v84, v68, s[98:99]
	v_cndmask_b32_e64 v153, v85, v69, s[98:99]
	v_cndmask_b32_e64 v154, v86, v70, s[98:99]
	v_cndmask_b32_e64 v155, v87, v71, s[98:99]
	v_fma_f32 v237, v100, v84, v80
	v_fma_f32 v238, v101, v85, v81
	v_fma_f32 v239, v102, v86, v82
	v_fma_f32 v240, v103, v87, v83
	v_fmac_f32_dpp v237, v148, v112 row_ror:1 row_mask:0xf bank_mask:0xf
	v_fmac_f32_dpp v238, v149, v113 row_ror:1 row_mask:0xf bank_mask:0xf
	v_fmac_f32_dpp v239, v150, v114 row_ror:1 row_mask:0xf bank_mask:0xf
	v_fmac_f32_dpp v240, v151, v115 row_ror:1 row_mask:0xf bank_mask:0xf
	v_fmac_f32_dpp v237, v152, v92 row_ror:15 row_mask:0xf bank_mask:0xf
	v_fmac_f32_dpp v238, v153, v93 row_ror:15 row_mask:0xf bank_mask:0xf
	v_fmac_f32_dpp v239, v154, v94 row_ror:15 row_mask:0xf bank_mask:0xf
	v_fmac_f32_dpp v240, v155, v95 row_ror:15 row_mask:0xf bank_mask:0xf
	v_mul_f32_e32 v148, 0xbfb8aa3b, v156
	v_mul_f32_e32 v149, 0xbfb8aa3b, v157
	v_mul_f32_e32 v150, 0xbfb8aa3b, v158
	v_mul_f32_e32 v151, 0xbfb8aa3b, v159
	v_exp_f32_e32 v148, v148
	v_exp_f32_e32 v149, v149
	v_exp_f32_e32 v150, v150
	v_exp_f32_e32 v151, v151
	v_add_f32_e32 v148, 1.0, v148
	v_add_f32_e32 v149, 1.0, v149
	v_add_f32_e32 v150, 1.0, v150
	v_add_f32_e32 v151, 1.0, v151
	v_rcp_f32_e32 v148, v148
	v_rcp_f32_e32 v149, v149
	v_rcp_f32_e32 v150, v150
	v_rcp_f32_e32 v151, v151
	v_mul_f32_e32 v156, v156, v148
	v_mul_f32_e32 v157, v157, v149
	v_mul_f32_e32 v158, v158, v150
	v_mul_f32_e32 v159, v159, v151
	v_mul_f32_e32 v156, v156, v237
	v_mul_f32_e32 v157, v157, v238
	v_mul_f32_e32 v158, v158, v239
	v_mul_f32_e32 v159, v159, v240
	v_cvt_pk_bf16_f32 v40, v156, v157
	v_cvt_pk_bf16_f32 v41, v158, v159
	v_bfi_b32 v18, v146, v241, v40
	v_bfi_b32 v19, v146, v242, v41
	ds_swizzle_b32 v16, v18 offset:0x401f
	ds_swizzle_b32 v17, v19 offset:0x401f
	v_mov_b32_e32 v42, v250
	v_lshrrev_b32_e32 v152, 6, v251
	s_nop 1
	v_readfirstlane_b32 s100, v152
	s_waitcnt lgkmcnt(0)
	v_bfi_b32 v148, v146, v16, v241
	v_bfi_b32 v149, v146, v17, v242
	v_bfi_b32 v150, v146, v40, v16
	v_bfi_b32 v151, v146, v41, v17
	s_cmp_eq_u32 s100, 0
	s_cselect_b64 s[100:101], s[98:99], 0
	s_andn2_b64 exec, exec, s[100:101]
	global_store_dwordx4 v42, v[148:151], s[12:13]
	s_mov_b64 exec, -1
	s_nop 1
	ds_read_b128 v[204:207], v249 offset:4160
	ds_read_b128 v[208:211], v249 offset:4672
	v_cndmask_b32_e32 v148, v96, v108, vcc
	v_cndmask_b32_e32 v149, v97, v109, vcc
	v_cndmask_b32_e32 v150, v98, v110, vcc
	v_cndmask_b32_e32 v151, v99, v111, vcc
	v_cndmask_b32_e64 v152, v96, v88, s[98:99]
	v_cndmask_b32_e64 v153, v97, v89, s[98:99]
	v_cndmask_b32_e64 v154, v98, v90, s[98:99]
	v_cndmask_b32_e64 v155, v99, v91, s[98:99]
	v_fma_f32 v156, v120, v96, v104
	v_fma_f32 v157, v121, v97, v105
	v_fma_f32 v158, v122, v98, v106
	v_fma_f32 v159, v123, v99, v107
	v_fmac_f32_dpp v156, v148, v124 row_ror:1 row_mask:0xf bank_mask:0xf
	v_fmac_f32_dpp v157, v149, v125 row_ror:1 row_mask:0xf bank_mask:0xf
	v_fmac_f32_dpp v158, v150, v126 row_ror:1 row_mask:0xf bank_mask:0xf
	v_fmac_f32_dpp v159, v151, v127 row_ror:1 row_mask:0xf bank_mask:0xf
	v_fmac_f32_dpp v156, v152, v116 row_ror:15 row_mask:0xf bank_mask:0xf
	v_fmac_f32_dpp v157, v153, v117 row_ror:15 row_mask:0xf bank_mask:0xf
	v_fmac_f32_dpp v158, v154, v118 row_ror:15 row_mask:0xf bank_mask:0xf
	v_fmac_f32_dpp v159, v155, v119 row_ror:15 row_mask:0xf bank_mask:0xf
	v_cndmask_b32_e32 v148, v68, v84, vcc
	v_cndmask_b32_e32 v149, v69, v85, vcc
	v_cndmask_b32_e32 v150, v70, v86, vcc
	v_cndmask_b32_e32 v151, v71, v87, vcc
	v_cndmask_b32_e64 v152, v68, v60, s[98:99]
	v_cndmask_b32_e64 v153, v69, v61, s[98:99]
	v_cndmask_b32_e64 v154, v70, v62, s[98:99]
	v_cndmask_b32_e64 v155, v71, v63, s[98:99]
	v_fma_f32 v237, v100, v68, v80
	v_fma_f32 v238, v101, v69, v81
	v_fma_f32 v239, v102, v70, v82
	v_fma_f32 v240, v103, v71, v83
	v_fmac_f32_dpp v237, v148, v112 row_ror:1 row_mask:0xf bank_mask:0xf
	v_fmac_f32_dpp v238, v149, v113 row_ror:1 row_mask:0xf bank_mask:0xf
	v_fmac_f32_dpp v239, v150, v114 row_ror:1 row_mask:0xf bank_mask:0xf
	v_fmac_f32_dpp v240, v151, v115 row_ror:1 row_mask:0xf bank_mask:0xf
	v_fmac_f32_dpp v237, v152, v92 row_ror:15 row_mask:0xf bank_mask:0xf
	v_fmac_f32_dpp v238, v153, v93 row_ror:15 row_mask:0xf bank_mask:0xf
	v_fmac_f32_dpp v239, v154, v94 row_ror:15 row_mask:0xf bank_mask:0xf
	v_fmac_f32_dpp v240, v155, v95 row_ror:15 row_mask:0xf bank_mask:0xf
	v_mul_f32_e32 v148, 0xbfb8aa3b, v156
	v_mul_f32_e32 v149, 0xbfb8aa3b, v157
	v_mul_f32_e32 v150, 0xbfb8aa3b, v158
	v_mul_f32_e32 v151, 0xbfb8aa3b, v159
	v_exp_f32_e32 v148, v148
	v_exp_f32_e32 v149, v149
	v_exp_f32_e32 v150, v150
	v_exp_f32_e32 v151, v151
	v_add_f32_e32 v148, 1.0, v148
	v_add_f32_e32 v149, 1.0, v149
	v_add_f32_e32 v150, 1.0, v150
	v_add_f32_e32 v151, 1.0, v151
	v_rcp_f32_e32 v148, v148
	v_rcp_f32_e32 v149, v149
	v_rcp_f32_e32 v150, v150
	v_rcp_f32_e32 v151, v151
	v_mul_f32_e32 v156, v156, v148
	v_mul_f32_e32 v157, v157, v149
	v_mul_f32_e32 v158, v158, v150
	v_mul_f32_e32 v159, v159, v151
	v_mul_f32_e32 v156, v156, v237
	v_mul_f32_e32 v157, v157, v238
	v_mul_f32_e32 v158, v158, v239
	v_mul_f32_e32 v159, v159, v240
	v_cvt_pk_bf16_f32 v40, v156, v157
	v_cvt_pk_bf16_f32 v41, v158, v159
	v_bfi_b32 v18, v146, v243, v40
	v_bfi_b32 v19, v146, v244, v41
	ds_swizzle_b32 v16, v18 offset:0x401f
	ds_swizzle_b32 v17, v19 offset:0x401f
	v_add_u32_e32 v42, 0x16000, v250
	s_waitcnt lgkmcnt(0)
	v_bfi_b32 v148, v146, v16, v243
	v_bfi_b32 v149, v146, v17, v244
	v_bfi_b32 v150, v146, v40, v16
	v_bfi_b32 v151, v146, v41, v17
	global_store_dwordx4 v42, v[148:151], s[12:13]
	s_nop 1
	v_cndmask_b32_e32 v148, v88, v96, vcc
	v_cndmask_b32_e32 v149, v89, v97, vcc
	v_cndmask_b32_e32 v150, v90, v98, vcc
	v_cndmask_b32_e32 v151, v91, v99, vcc
	v_cndmask_b32_e64 v152, v88, v76, s[98:99]
	v_cndmask_b32_e64 v153, v89, v77, s[98:99]
	v_cndmask_b32_e64 v154, v90, v78, s[98:99]
	v_cndmask_b32_e64 v155, v91, v79, s[98:99]
	v_fma_f32 v156, v120, v88, v104
	v_fma_f32 v157, v121, v89, v105
	v_fma_f32 v158, v122, v90, v106
	v_fma_f32 v159, v123, v91, v107
	v_fmac_f32_dpp v156, v148, v124 row_ror:1 row_mask:0xf bank_mask:0xf
	v_fmac_f32_dpp v157, v149, v125 row_ror:1 row_mask:0xf bank_mask:0xf
	v_fmac_f32_dpp v158, v150, v126 row_ror:1 row_mask:0xf bank_mask:0xf
	v_fmac_f32_dpp v159, v151, v127 row_ror:1 row_mask:0xf bank_mask:0xf
	v_fmac_f32_dpp v156, v152, v116 row_ror:15 row_mask:0xf bank_mask:0xf
	v_fmac_f32_dpp v157, v153, v117 row_ror:15 row_mask:0xf bank_mask:0xf
	v_fmac_f32_dpp v158, v154, v118 row_ror:15 row_mask:0xf bank_mask:0xf
	v_fmac_f32_dpp v159, v155, v119 row_ror:15 row_mask:0xf bank_mask:0xf
	v_cndmask_b32_e32 v148, v60, v68, vcc
	v_cndmask_b32_e32 v149, v61, v69, vcc
	v_cndmask_b32_e32 v150, v62, v70, vcc
	v_cndmask_b32_e32 v151, v63, v71, vcc
	v_cndmask_b32_e64 v152, v60, v52, s[98:99]
	v_cndmask_b32_e64 v153, v61, v53, s[98:99]
	v_cndmask_b32_e64 v154, v62, v54, s[98:99]
	v_cndmask_b32_e64 v155, v63, v55, s[98:99]
	v_fma_f32 v237, v100, v60, v80
	v_fma_f32 v238, v101, v61, v81
	v_fma_f32 v239, v102, v62, v82
	v_fma_f32 v240, v103, v63, v83
	v_fmac_f32_dpp v237, v148, v112 row_ror:1 row_mask:0xf bank_mask:0xf
	v_fmac_f32_dpp v238, v149, v113 row_ror:1 row_mask:0xf bank_mask:0xf
	v_fmac_f32_dpp v239, v150, v114 row_ror:1 row_mask:0xf bank_mask:0xf
	v_fmac_f32_dpp v240, v151, v115 row_ror:1 row_mask:0xf bank_mask:0xf
	v_fmac_f32_dpp v237, v152, v92 row_ror:15 row_mask:0xf bank_mask:0xf
	v_fmac_f32_dpp v238, v153, v93 row_ror:15 row_mask:0xf bank_mask:0xf
	v_fmac_f32_dpp v239, v154, v94 row_ror:15 row_mask:0xf bank_mask:0xf
	v_fmac_f32_dpp v240, v155, v95 row_ror:15 row_mask:0xf bank_mask:0xf
	v_mul_f32_e32 v148, 0xbfb8aa3b, v156
	v_mul_f32_e32 v149, 0xbfb8aa3b, v157
	v_mul_f32_e32 v150, 0xbfb8aa3b, v158
	v_mul_f32_e32 v151, 0xbfb8aa3b, v159
	v_exp_f32_e32 v148, v148
	v_exp_f32_e32 v149, v149
	v_exp_f32_e32 v150, v150
	v_exp_f32_e32 v151, v151
	v_add_f32_e32 v148, 1.0, v148
	v_add_f32_e32 v149, 1.0, v149
	v_add_f32_e32 v150, 1.0, v150
	v_add_f32_e32 v151, 1.0, v151
	v_rcp_f32_e32 v148, v148
	v_rcp_f32_e32 v149, v149
	v_rcp_f32_e32 v150, v150
	v_rcp_f32_e32 v151, v151
	v_mul_f32_e32 v156, v156, v148
	v_mul_f32_e32 v157, v157, v149
	v_mul_f32_e32 v158, v158, v150
	v_mul_f32_e32 v159, v159, v151
	v_mul_f32_e32 v156, v156, v237
	v_mul_f32_e32 v157, v157, v238
	v_mul_f32_e32 v158, v158, v239
	v_mul_f32_e32 v159, v159, v240
	v_cvt_pk_bf16_f32 v40, v156, v157
	v_cvt_pk_bf16_f32 v41, v158, v159
	v_bfi_b32 v18, v146, v253, v40
	v_bfi_b32 v19, v146, v254, v41
	ds_swizzle_b32 v16, v18 offset:0x401f
	ds_swizzle_b32 v17, v19 offset:0x401f
	v_add_u32_e32 v42, 0x2c000, v250
	s_waitcnt lgkmcnt(0)
	v_bfi_b32 v148, v146, v16, v253
	v_bfi_b32 v149, v146, v17, v254
	v_bfi_b32 v150, v146, v40, v16
	v_bfi_b32 v151, v146, v41, v17
	global_store_dwordx4 v42, v[148:151], s[12:13]
	s_nop 1
	v_cndmask_b32_e32 v148, v76, v88, vcc
	v_cndmask_b32_e32 v149, v77, v89, vcc
	v_cndmask_b32_e32 v150, v78, v90, vcc
	v_cndmask_b32_e32 v151, v79, v91, vcc
	v_cndmask_b32_e64 v152, v76, v160, s[98:99]
	v_cndmask_b32_e64 v153, v77, v161, s[98:99]
	v_cndmask_b32_e64 v154, v78, v162, s[98:99]
	v_cndmask_b32_e64 v155, v79, v163, s[98:99]
	v_fma_f32 v156, v120, v76, v104
	v_fma_f32 v157, v121, v77, v105
	v_fma_f32 v158, v122, v78, v106
	v_fma_f32 v159, v123, v79, v107
	v_fmac_f32_dpp v156, v148, v124 row_ror:1 row_mask:0xf bank_mask:0xf
	v_fmac_f32_dpp v157, v149, v125 row_ror:1 row_mask:0xf bank_mask:0xf
	v_fmac_f32_dpp v158, v150, v126 row_ror:1 row_mask:0xf bank_mask:0xf
	v_fmac_f32_dpp v159, v151, v127 row_ror:1 row_mask:0xf bank_mask:0xf
	v_fmac_f32_dpp v156, v152, v116 row_ror:15 row_mask:0xf bank_mask:0xf
	v_fmac_f32_dpp v157, v153, v117 row_ror:15 row_mask:0xf bank_mask:0xf
	v_fmac_f32_dpp v158, v154, v118 row_ror:15 row_mask:0xf bank_mask:0xf
	v_fmac_f32_dpp v159, v155, v119 row_ror:15 row_mask:0xf bank_mask:0xf
	v_cndmask_b32_e32 v148, v52, v60, vcc
	v_cndmask_b32_e32 v149, v53, v61, vcc
	v_cndmask_b32_e32 v150, v54, v62, vcc
	v_cndmask_b32_e32 v151, v55, v63, vcc
	v_cndmask_b32_e64 v152, v52, v164, s[98:99]
	v_cndmask_b32_e64 v153, v53, v165, s[98:99]
	v_cndmask_b32_e64 v154, v54, v166, s[98:99]
	v_cndmask_b32_e64 v155, v55, v167, s[98:99]
	v_fma_f32 v237, v100, v52, v80
	v_fma_f32 v238, v101, v53, v81
	v_fma_f32 v239, v102, v54, v82
	v_fma_f32 v240, v103, v55, v83
	v_fmac_f32_dpp v237, v148, v112 row_ror:1 row_mask:0xf bank_mask:0xf
	v_fmac_f32_dpp v238, v149, v113 row_ror:1 row_mask:0xf bank_mask:0xf
	v_fmac_f32_dpp v239, v150, v114 row_ror:1 row_mask:0xf bank_mask:0xf
	v_fmac_f32_dpp v240, v151, v115 row_ror:1 row_mask:0xf bank_mask:0xf
	v_fmac_f32_dpp v237, v152, v92 row_ror:15 row_mask:0xf bank_mask:0xf
	v_fmac_f32_dpp v238, v153, v93 row_ror:15 row_mask:0xf bank_mask:0xf
	v_fmac_f32_dpp v239, v154, v94 row_ror:15 row_mask:0xf bank_mask:0xf
	v_fmac_f32_dpp v240, v155, v95 row_ror:15 row_mask:0xf bank_mask:0xf
	v_mul_f32_e32 v148, 0xbfb8aa3b, v156
	v_mul_f32_e32 v149, 0xbfb8aa3b, v157
	v_mul_f32_e32 v150, 0xbfb8aa3b, v158
	v_mul_f32_e32 v151, 0xbfb8aa3b, v159
	v_exp_f32_e32 v148, v148
	v_exp_f32_e32 v149, v149
	v_exp_f32_e32 v150, v150
	v_exp_f32_e32 v151, v151
	v_add_f32_e32 v148, 1.0, v148
	v_add_f32_e32 v149, 1.0, v149
	v_add_f32_e32 v150, 1.0, v150
	v_add_f32_e32 v151, 1.0, v151
	v_rcp_f32_e32 v148, v148
	v_rcp_f32_e32 v149, v149
	v_rcp_f32_e32 v150, v150
	v_rcp_f32_e32 v151, v151
	v_mul_f32_e32 v156, v156, v148
	v_mul_f32_e32 v157, v157, v149
	v_mul_f32_e32 v158, v158, v150
	v_mul_f32_e32 v159, v159, v151
	v_mul_f32_e32 v156, v156, v237
	v_mul_f32_e32 v157, v157, v238
	v_mul_f32_e32 v158, v158, v239
	v_mul_f32_e32 v159, v159, v240
	v_cvt_pk_bf16_f32 v40, v156, v157
	v_cvt_pk_bf16_f32 v41, v158, v159
	v_bfi_b32 v18, v146, v255, v40
	v_bfi_b32 v19, v146, v246, v41
	ds_swizzle_b32 v16, v18 offset:0x401f
	ds_swizzle_b32 v17, v19 offset:0x401f
	v_add_u32_e32 v42, 0x42000, v250
	s_waitcnt lgkmcnt(0)
	v_bfi_b32 v148, v146, v16, v255
	v_bfi_b32 v149, v146, v17, v246
	v_bfi_b32 v150, v146, v40, v16
	v_bfi_b32 v151, v146, v41, v17
	global_store_dwordx4 v42, v[148:151], s[12:13]
	s_nop 1
	ds_read_b128 v[160:163], v249 offset:7232
	ds_read_b128 v[164:167], v249 offset:7744
	s_waitcnt lgkmcnt(2)
	v_cndmask_b32_e32 v148, v44, v204, vcc
	v_cndmask_b32_e32 v149, v45, v205, vcc
	v_cndmask_b32_e32 v150, v46, v206, vcc
	v_cndmask_b32_e32 v151, v47, v207, vcc
	v_cndmask_b32_e64 v152, v44, v32, s[98:99]
	v_cndmask_b32_e64 v153, v45, v33, s[98:99]
	v_cndmask_b32_e64 v154, v46, v34, s[98:99]
	v_cndmask_b32_e64 v155, v47, v35, s[98:99]
	v_fma_f32 v156, v120, v44, v104
	v_fma_f32 v157, v121, v45, v105
	v_fma_f32 v158, v122, v46, v106
	v_fma_f32 v159, v123, v47, v107
	v_fmac_f32_dpp v156, v148, v124 row_ror:1 row_mask:0xf bank_mask:0xf
	v_fmac_f32_dpp v157, v149, v125 row_ror:1 row_mask:0xf bank_mask:0xf
	v_fmac_f32_dpp v158, v150, v126 row_ror:1 row_mask:0xf bank_mask:0xf
	v_fmac_f32_dpp v159, v151, v127 row_ror:1 row_mask:0xf bank_mask:0xf
	v_fmac_f32_dpp v156, v152, v116 row_ror:15 row_mask:0xf bank_mask:0xf
	v_fmac_f32_dpp v157, v153, v117 row_ror:15 row_mask:0xf bank_mask:0xf
	v_fmac_f32_dpp v158, v154, v118 row_ror:15 row_mask:0xf bank_mask:0xf
	v_fmac_f32_dpp v159, v155, v119 row_ror:15 row_mask:0xf bank_mask:0xf
	v_cndmask_b32_e32 v148, v20, v208, vcc
	v_cndmask_b32_e32 v149, v21, v209, vcc
	v_cndmask_b32_e32 v150, v22, v210, vcc
	v_cndmask_b32_e32 v151, v23, v211, vcc
	v_cndmask_b32_e64 v152, v20, v8, s[98:99]
	v_cndmask_b32_e64 v153, v21, v9, s[98:99]
	v_cndmask_b32_e64 v154, v22, v10, s[98:99]
	v_cndmask_b32_e64 v155, v23, v11, s[98:99]
	v_fma_f32 v237, v100, v20, v80
	v_fma_f32 v238, v101, v21, v81
	v_fma_f32 v239, v102, v22, v82
	v_fma_f32 v240, v103, v23, v83
	v_fmac_f32_dpp v237, v148, v112 row_ror:1 row_mask:0xf bank_mask:0xf
	v_fmac_f32_dpp v238, v149, v113 row_ror:1 row_mask:0xf bank_mask:0xf
	v_fmac_f32_dpp v239, v150, v114 row_ror:1 row_mask:0xf bank_mask:0xf
	v_fmac_f32_dpp v240, v151, v115 row_ror:1 row_mask:0xf bank_mask:0xf
	v_fmac_f32_dpp v237, v152, v92 row_ror:15 row_mask:0xf bank_mask:0xf
	v_fmac_f32_dpp v238, v153, v93 row_ror:15 row_mask:0xf bank_mask:0xf
	v_fmac_f32_dpp v239, v154, v94 row_ror:15 row_mask:0xf bank_mask:0xf
	v_fmac_f32_dpp v240, v155, v95 row_ror:15 row_mask:0xf bank_mask:0xf
	v_mul_f32_e32 v148, 0xbfb8aa3b, v156
	v_mul_f32_e32 v149, 0xbfb8aa3b, v157
	v_mul_f32_e32 v150, 0xbfb8aa3b, v158
	v_mul_f32_e32 v151, 0xbfb8aa3b, v159
	v_exp_f32_e32 v148, v148
	v_exp_f32_e32 v149, v149
	v_exp_f32_e32 v150, v150
	v_exp_f32_e32 v151, v151
	v_add_f32_e32 v148, 1.0, v148
	v_add_f32_e32 v149, 1.0, v149
	v_add_f32_e32 v150, 1.0, v150
	v_add_f32_e32 v151, 1.0, v151
	v_rcp_f32_e32 v148, v148
	v_rcp_f32_e32 v149, v149
	v_rcp_f32_e32 v150, v150
	v_rcp_f32_e32 v151, v151
	v_mul_f32_e32 v156, v156, v148
	v_mul_f32_e32 v157, v157, v149
	v_mul_f32_e32 v158, v158, v150
	v_mul_f32_e32 v159, v159, v151
	v_mul_f32_e32 v156, v156, v237
	v_mul_f32_e32 v157, v157, v238
	v_mul_f32_e32 v158, v158, v239
	v_mul_f32_e32 v159, v159, v240
	v_cvt_pk_bf16_f32 v40, v156, v157
	v_cvt_pk_bf16_f32 v41, v158, v159
	v_bfi_b32 v18, v146, v247, v40
	v_bfi_b32 v19, v146, v248, v41
	ds_swizzle_b32 v16, v18 offset:0x401f
	ds_swizzle_b32 v17, v19 offset:0x401f
	v_add_u32_e32 v42, 0xb0000, v250
	s_waitcnt lgkmcnt(0)
	v_bfi_b32 v148, v146, v16, v247
	v_bfi_b32 v149, v146, v17, v248
	v_bfi_b32 v150, v146, v40, v16
	v_bfi_b32 v151, v146, v41, v17
	global_store_dwordx4 v42, v[148:151], s[12:13]
	s_nop 1
	v_cndmask_b32_e32 v148, v32, v44, vcc
	v_cndmask_b32_e32 v149, v33, v45, vcc
	v_cndmask_b32_e32 v150, v34, v46, vcc
	v_cndmask_b32_e32 v151, v35, v47, vcc
	v_cndmask_b32_e64 v152, v32, v24, s[98:99]
	v_cndmask_b32_e64 v153, v33, v25, s[98:99]
	v_cndmask_b32_e64 v154, v34, v26, s[98:99]
	v_cndmask_b32_e64 v155, v35, v27, s[98:99]
	v_fma_f32 v156, v120, v32, v104
	v_fma_f32 v157, v121, v33, v105
	v_fma_f32 v158, v122, v34, v106
	v_fma_f32 v159, v123, v35, v107
	v_fmac_f32_dpp v156, v148, v124 row_ror:1 row_mask:0xf bank_mask:0xf
	v_fmac_f32_dpp v157, v149, v125 row_ror:1 row_mask:0xf bank_mask:0xf
	v_fmac_f32_dpp v158, v150, v126 row_ror:1 row_mask:0xf bank_mask:0xf
	v_fmac_f32_dpp v159, v151, v127 row_ror:1 row_mask:0xf bank_mask:0xf
	v_fmac_f32_dpp v156, v152, v116 row_ror:15 row_mask:0xf bank_mask:0xf
	v_fmac_f32_dpp v157, v153, v117 row_ror:15 row_mask:0xf bank_mask:0xf
	v_fmac_f32_dpp v158, v154, v118 row_ror:15 row_mask:0xf bank_mask:0xf
	v_fmac_f32_dpp v159, v155, v119 row_ror:15 row_mask:0xf bank_mask:0xf
	v_cndmask_b32_e32 v148, v8, v20, vcc
	v_cndmask_b32_e32 v149, v9, v21, vcc
	v_cndmask_b32_e32 v150, v10, v22, vcc
	v_cndmask_b32_e32 v151, v11, v23, vcc
	v_cndmask_b32_e64 v152, v8, v4, s[98:99]
	v_cndmask_b32_e64 v153, v9, v5, s[98:99]
	v_cndmask_b32_e64 v154, v10, v6, s[98:99]
	v_cndmask_b32_e64 v155, v11, v7, s[98:99]
	v_fma_f32 v237, v100, v8, v80
	v_fma_f32 v238, v101, v9, v81
	v_fma_f32 v239, v102, v10, v82
	v_fma_f32 v240, v103, v11, v83
	v_fmac_f32_dpp v237, v148, v112 row_ror:1 row_mask:0xf bank_mask:0xf
	v_fmac_f32_dpp v238, v149, v113 row_ror:1 row_mask:0xf bank_mask:0xf
	v_fmac_f32_dpp v239, v150, v114 row_ror:1 row_mask:0xf bank_mask:0xf
	v_fmac_f32_dpp v240, v151, v115 row_ror:1 row_mask:0xf bank_mask:0xf
	v_fmac_f32_dpp v237, v152, v92 row_ror:15 row_mask:0xf bank_mask:0xf
	v_fmac_f32_dpp v238, v153, v93 row_ror:15 row_mask:0xf bank_mask:0xf
	v_fmac_f32_dpp v239, v154, v94 row_ror:15 row_mask:0xf bank_mask:0xf
	v_fmac_f32_dpp v240, v155, v95 row_ror:15 row_mask:0xf bank_mask:0xf
	v_mul_f32_e32 v148, 0xbfb8aa3b, v156
	v_mul_f32_e32 v149, 0xbfb8aa3b, v157
	v_mul_f32_e32 v150, 0xbfb8aa3b, v158
	v_mul_f32_e32 v151, 0xbfb8aa3b, v159
	v_exp_f32_e32 v148, v148
	v_exp_f32_e32 v149, v149
	v_exp_f32_e32 v150, v150
	v_exp_f32_e32 v151, v151
	v_add_f32_e32 v148, 1.0, v148
	v_add_f32_e32 v149, 1.0, v149
	v_add_f32_e32 v150, 1.0, v150
	v_add_f32_e32 v151, 1.0, v151
	v_rcp_f32_e32 v148, v148
	v_rcp_f32_e32 v149, v149
	v_rcp_f32_e32 v150, v150
	v_rcp_f32_e32 v151, v151
	v_mul_f32_e32 v156, v156, v148
	v_mul_f32_e32 v157, v157, v149
	v_mul_f32_e32 v158, v158, v150
	v_mul_f32_e32 v159, v159, v151
	v_mul_f32_e32 v156, v156, v237
	v_mul_f32_e32 v157, v157, v238
	v_mul_f32_e32 v158, v158, v239
	v_mul_f32_e32 v159, v159, v240
	v_cvt_pk_bf16_f32 v40, v156, v157
	v_cvt_pk_bf16_f32 v41, v158, v159
	v_bfi_b32 v18, v146, v72, v40
	v_bfi_b32 v19, v146, v73, v41
	ds_swizzle_b32 v16, v18 offset:0x401f
	ds_swizzle_b32 v17, v19 offset:0x401f
	v_add_u32_e32 v42, 0xc6000, v250
	s_waitcnt lgkmcnt(0)
	v_bfi_b32 v148, v146, v16, v72
	v_bfi_b32 v149, v146, v17, v73
	v_bfi_b32 v150, v146, v40, v16
	v_bfi_b32 v151, v146, v41, v17
	global_store_dwordx4 v42, v[148:151], s[12:13]
	s_nop 1
	v_cndmask_b32_e32 v148, v24, v32, vcc
	v_cndmask_b32_e32 v149, v25, v33, vcc
	v_cndmask_b32_e32 v150, v26, v34, vcc
	v_cndmask_b32_e32 v151, v27, v35, vcc
	v_cndmask_b32_e64 v152, v24, v12, s[98:99]
	v_cndmask_b32_e64 v153, v25, v13, s[98:99]
	v_cndmask_b32_e64 v154, v26, v14, s[98:99]
	v_cndmask_b32_e64 v155, v27, v15, s[98:99]
	v_fma_f32 v156, v120, v24, v104
	v_fma_f32 v157, v121, v25, v105
	v_fma_f32 v158, v122, v26, v106
	v_fma_f32 v159, v123, v27, v107
	v_fmac_f32_dpp v156, v148, v124 row_ror:1 row_mask:0xf bank_mask:0xf
	v_fmac_f32_dpp v157, v149, v125 row_ror:1 row_mask:0xf bank_mask:0xf
	v_fmac_f32_dpp v158, v150, v126 row_ror:1 row_mask:0xf bank_mask:0xf
	v_fmac_f32_dpp v159, v151, v127 row_ror:1 row_mask:0xf bank_mask:0xf
	v_fmac_f32_dpp v156, v152, v116 row_ror:15 row_mask:0xf bank_mask:0xf
	v_fmac_f32_dpp v157, v153, v117 row_ror:15 row_mask:0xf bank_mask:0xf
	v_fmac_f32_dpp v158, v154, v118 row_ror:15 row_mask:0xf bank_mask:0xf
	v_fmac_f32_dpp v159, v155, v119 row_ror:15 row_mask:0xf bank_mask:0xf
	v_cndmask_b32_e32 v148, v4, v8, vcc
	v_cndmask_b32_e32 v149, v5, v9, vcc
	v_cndmask_b32_e32 v150, v6, v10, vcc
	v_cndmask_b32_e32 v151, v7, v11, vcc
	v_cndmask_b32_e64 v152, v4, v0, s[98:99]
	v_cndmask_b32_e64 v153, v5, v1, s[98:99]
	v_cndmask_b32_e64 v154, v6, v2, s[98:99]
	v_cndmask_b32_e64 v155, v7, v3, s[98:99]
	v_fma_f32 v237, v100, v4, v80
	v_fma_f32 v238, v101, v5, v81
	v_fma_f32 v239, v102, v6, v82
	v_fma_f32 v240, v103, v7, v83
	v_fmac_f32_dpp v237, v148, v112 row_ror:1 row_mask:0xf bank_mask:0xf
	v_fmac_f32_dpp v238, v149, v113 row_ror:1 row_mask:0xf bank_mask:0xf
	v_fmac_f32_dpp v239, v150, v114 row_ror:1 row_mask:0xf bank_mask:0xf
	v_fmac_f32_dpp v240, v151, v115 row_ror:1 row_mask:0xf bank_mask:0xf
	v_fmac_f32_dpp v237, v152, v92 row_ror:15 row_mask:0xf bank_mask:0xf
	v_fmac_f32_dpp v238, v153, v93 row_ror:15 row_mask:0xf bank_mask:0xf
	v_fmac_f32_dpp v239, v154, v94 row_ror:15 row_mask:0xf bank_mask:0xf
	v_fmac_f32_dpp v240, v155, v95 row_ror:15 row_mask:0xf bank_mask:0xf
	v_mul_f32_e32 v148, 0xbfb8aa3b, v156
	v_mul_f32_e32 v149, 0xbfb8aa3b, v157
	v_mul_f32_e32 v150, 0xbfb8aa3b, v158
	v_mul_f32_e32 v151, 0xbfb8aa3b, v159
	v_exp_f32_e32 v148, v148
	v_exp_f32_e32 v149, v149
	v_exp_f32_e32 v150, v150
	v_exp_f32_e32 v151, v151
	v_add_f32_e32 v148, 1.0, v148
	v_add_f32_e32 v149, 1.0, v149
	v_add_f32_e32 v150, 1.0, v150
	v_add_f32_e32 v151, 1.0, v151
	v_rcp_f32_e32 v148, v148
	v_rcp_f32_e32 v149, v149
	v_rcp_f32_e32 v150, v150
	v_rcp_f32_e32 v151, v151
	v_mul_f32_e32 v156, v156, v148
	v_mul_f32_e32 v157, v157, v149
	v_mul_f32_e32 v158, v158, v150
	v_mul_f32_e32 v159, v159, v151
	v_mul_f32_e32 v156, v156, v237
	v_mul_f32_e32 v157, v157, v238
	v_mul_f32_e32 v158, v158, v239
	v_mul_f32_e32 v159, v159, v240
	v_cvt_pk_bf16_f32 v40, v156, v157
	v_cvt_pk_bf16_f32 v41, v158, v159
	v_bfi_b32 v18, v146, v74, v40
	v_bfi_b32 v19, v146, v75, v41
	ds_swizzle_b32 v16, v18 offset:0x401f
	ds_swizzle_b32 v17, v19 offset:0x401f
	v_add_u32_e32 v42, 0xdc000, v250
	s_waitcnt lgkmcnt(0)
	v_bfi_b32 v148, v146, v16, v74
	v_bfi_b32 v149, v146, v17, v75
	v_bfi_b32 v150, v146, v40, v16
	v_bfi_b32 v151, v146, v41, v17
	global_store_dwordx4 v42, v[148:151], s[12:13]
	s_nop 1
	s_waitcnt lgkmcnt(0)
	v_cndmask_b32_e32 v148, v12, v24, vcc
	v_cndmask_b32_e32 v149, v13, v25, vcc
	v_cndmask_b32_e32 v150, v14, v26, vcc
	v_cndmask_b32_e32 v151, v15, v27, vcc
	v_cndmask_b32_e64 v152, v12, v160, s[98:99]
	v_cndmask_b32_e64 v153, v13, v161, s[98:99]
	v_cndmask_b32_e64 v154, v14, v162, s[98:99]
	v_cndmask_b32_e64 v155, v15, v163, s[98:99]
	v_fma_f32 v156, v120, v12, v104
	v_fma_f32 v157, v121, v13, v105
	v_fma_f32 v158, v122, v14, v106
	v_fma_f32 v159, v123, v15, v107
	v_fmac_f32_dpp v156, v148, v124 row_ror:1 row_mask:0xf bank_mask:0xf
	v_fmac_f32_dpp v157, v149, v125 row_ror:1 row_mask:0xf bank_mask:0xf
	v_fmac_f32_dpp v158, v150, v126 row_ror:1 row_mask:0xf bank_mask:0xf
	v_fmac_f32_dpp v159, v151, v127 row_ror:1 row_mask:0xf bank_mask:0xf
	v_fmac_f32_dpp v156, v152, v116 row_ror:15 row_mask:0xf bank_mask:0xf
	v_fmac_f32_dpp v157, v153, v117 row_ror:15 row_mask:0xf bank_mask:0xf
	v_fmac_f32_dpp v158, v154, v118 row_ror:15 row_mask:0xf bank_mask:0xf
	v_fmac_f32_dpp v159, v155, v119 row_ror:15 row_mask:0xf bank_mask:0xf
	v_cndmask_b32_e32 v148, v0, v4, vcc
	v_cndmask_b32_e32 v149, v1, v5, vcc
	v_cndmask_b32_e32 v150, v2, v6, vcc
	v_cndmask_b32_e32 v151, v3, v7, vcc
	v_cndmask_b32_e64 v152, v0, v164, s[98:99]
	v_cndmask_b32_e64 v153, v1, v165, s[98:99]
	v_cndmask_b32_e64 v154, v2, v166, s[98:99]
	v_cndmask_b32_e64 v155, v3, v167, s[98:99]
	v_fma_f32 v237, v100, v0, v80
	v_fma_f32 v238, v101, v1, v81
	v_fma_f32 v239, v102, v2, v82
	v_fma_f32 v240, v103, v3, v83
	v_fmac_f32_dpp v237, v148, v112 row_ror:1 row_mask:0xf bank_mask:0xf
	v_fmac_f32_dpp v238, v149, v113 row_ror:1 row_mask:0xf bank_mask:0xf
	v_fmac_f32_dpp v239, v150, v114 row_ror:1 row_mask:0xf bank_mask:0xf
	v_fmac_f32_dpp v240, v151, v115 row_ror:1 row_mask:0xf bank_mask:0xf
	v_fmac_f32_dpp v237, v152, v92 row_ror:15 row_mask:0xf bank_mask:0xf
	v_fmac_f32_dpp v238, v153, v93 row_ror:15 row_mask:0xf bank_mask:0xf
	v_fmac_f32_dpp v239, v154, v94 row_ror:15 row_mask:0xf bank_mask:0xf
	v_fmac_f32_dpp v240, v155, v95 row_ror:15 row_mask:0xf bank_mask:0xf
	v_mul_f32_e32 v148, 0xbfb8aa3b, v156
	v_mul_f32_e32 v149, 0xbfb8aa3b, v157
	v_mul_f32_e32 v150, 0xbfb8aa3b, v158
	v_mul_f32_e32 v151, 0xbfb8aa3b, v159
	v_exp_f32_e32 v148, v148
	v_exp_f32_e32 v149, v149
	v_exp_f32_e32 v150, v150
	v_exp_f32_e32 v151, v151
	v_add_f32_e32 v148, 1.0, v148
	v_add_f32_e32 v149, 1.0, v149
	v_add_f32_e32 v150, 1.0, v150
	v_add_f32_e32 v151, 1.0, v151
	v_rcp_f32_e32 v148, v148
	v_rcp_f32_e32 v149, v149
	v_rcp_f32_e32 v150, v150
	v_rcp_f32_e32 v151, v151
	v_mul_f32_e32 v156, v156, v148
	v_mul_f32_e32 v157, v157, v149
	v_mul_f32_e32 v158, v158, v150
	v_mul_f32_e32 v159, v159, v151
	v_mul_f32_e32 v156, v156, v237
	v_mul_f32_e32 v157, v157, v238
	v_mul_f32_e32 v158, v158, v239
	v_mul_f32_e32 v159, v159, v240
	v_cvt_pk_bf16_f32 v40, v156, v157
	v_cvt_pk_bf16_f32 v41, v158, v159
	v_bfi_b32 v18, v146, v48, v40
	v_bfi_b32 v19, v146, v49, v41
	ds_swizzle_b32 v16, v18 offset:0x401f
	ds_swizzle_b32 v17, v19 offset:0x401f
	v_add_u32_e32 v42, 0xf2000, v250
	v_lshrrev_b32_e32 v152, 6, v251
	s_nop 1
	v_readfirstlane_b32 s100, v152
	s_waitcnt lgkmcnt(0)
	v_bfi_b32 v148, v146, v16, v48
	v_bfi_b32 v149, v146, v17, v49
	v_bfi_b32 v150, v146, v40, v16
	v_bfi_b32 v151, v146, v41, v17
	s_cmp_eq_u32 s100, 1
	s_cselect_b64 s[100:101], vcc, 0
	s_andn2_b64 exec, exec, s[100:101]
	global_store_dwordx4 v42, v[148:151], s[12:13]
	s_mov_b64 exec, -1
	s_nop 1
	s_branch .LBB0_2210
